# adds: K-loop MFMA blocks open with the barrier (the one MFMA the compiler hoisted above each opening barrier moved back below it)
# speedup vs baseline: 1.0042x; 1.0042x over previous
.LBB0_244:
	s_ashr_i32 s73, s72, 31
	s_lshl_b64 s[74:75], s[72:73], 19
	s_add_u32 s74, s24, s74
	s_addc_u32 s75, s25, s75
	s_and_b64 s[76:77], s[4:5], exec
	s_cselect_b32 s0, s75, s81
	s_cselect_b32 s7, s74, s80
	s_ashr_i32 s47, s46, 31
	s_lshl_b64 s[76:77], s[46:47], 19
	s_add_u32 s76, s70, s76
	s_addc_u32 s77, s71, s77
	s_and_b64 s[84:85], s[4:5], exec
	s_cselect_b32 s47, s77, s83
	s_cselect_b32 s73, s76, s82
	s_add_u32 s80, s80, 0x40080
	s_addc_u32 s81, s81, 0
	s_add_u32 s93, s82, 0x100
	s_addc_u32 s94, s83, 0
	s_mov_b32 s95, -2
	ds_read_b128 v[130:133], v161
	ds_read_b128 v[134:137], v161 offset:1024
	ds_read_b128 v[164:167], v161 offset:2048
	ds_read_b128 v[168:171], v161 offset:3072
	ds_read_b128 v[172:175], v162
	ds_read_b128 v[176:179], v162 offset:1024
	ds_read_b128 v[180:183], v162 offset:2048
	ds_read_b128 v[184:187], v162 offset:3072
	s_add_u32 s82, s80, 0xfffc0080
	s_addc_u32 s83, s81, -1
	s_cmp_eq_u32 s95, 12
	s_cselect_b32 s85, s0, s83
	s_cselect_b32 s84, s7, s82
	s_cselect_b32 s83, s47, s94
	s_cselect_b32 s82, s73, s93
	v_lshl_add_u64 v[220:221], s[80:81], 0, v[150:151]
	s_add_i32 m0, s27, 0xc000
	ds_read_b128 v[188:191], v163
	ds_read_b128 v[192:195], v163 offset:1024
	ds_read_b128 v[196:199], v163 offset:2048
	ds_read_b128 v[200:203], v163 offset:3072
	ds_read_b128 v[204:207], v163 offset:4096
	ds_read_b128 v[208:211], v163 offset:5120
	ds_read_b128 v[212:215], v163 offset:6144
	ds_read_b128 v[216:219], v163 offset:7168
	global_load_lds_dwordx4 v[220:221], off
	v_lshl_add_u64 v[220:221], s[80:81], 0, v[152:153]
	s_add_i32 m0, s27, 0xe000
	s_nop 0
	global_load_lds_dwordx4 v[220:221], off
	s_waitcnt vmcnt(8)
	s_waitcnt lgkmcnt(0)
	s_setprio 1
	s_waitcnt lgkmcnt(0)
	s_barrier
	v_mfma_f32_16x16x32_bf16 v[126:129], v[130:133], v[188:191], 0
	v_mfma_f32_16x16x32_bf16 v[122:125], v[164:167], v[188:191], 0
	v_mfma_f32_16x16x32_bf16 v[118:121], v[130:133], v[196:199], 0
	v_mfma_f32_16x16x32_bf16 v[110:113], v[164:167], v[196:199], 0
	v_mfma_f32_16x16x32_bf16 v[102:105], v[130:133], v[204:207], 0
	v_mfma_f32_16x16x32_bf16 v[94:97], v[164:167], v[204:207], 0
	v_mfma_f32_16x16x32_bf16 v[86:89], v[130:133], v[212:215], 0
	v_mfma_f32_16x16x32_bf16 v[78:81], v[164:167], v[212:215], 0
	v_mfma_f32_16x16x32_bf16 v[114:117], v[172:175], v[188:191], 0
	v_mfma_f32_16x16x32_bf16 v[106:109], v[180:183], v[188:191], 0
	v_mfma_f32_16x16x32_bf16 v[98:101], v[172:175], v[196:199], 0
	v_mfma_f32_16x16x32_bf16 v[90:93], v[180:183], v[196:199], 0
	v_mfma_f32_16x16x32_bf16 v[82:85], v[172:175], v[204:207], 0
	v_mfma_f32_16x16x32_bf16 v[74:77], v[180:183], v[204:207], 0
	v_mfma_f32_16x16x32_bf16 v[70:73], v[172:175], v[212:215], 0
	v_mfma_f32_16x16x32_bf16 v[66:69], v[180:183], v[212:215], 0
	v_mfma_f32_16x16x32_bf16 v[126:129], v[134:137], v[192:195], v[126:129]
	v_mfma_f32_16x16x32_bf16 v[122:125], v[168:171], v[192:195], v[122:125]
	v_mfma_f32_16x16x32_bf16 v[118:121], v[134:137], v[200:203], v[118:121]
	v_mfma_f32_16x16x32_bf16 v[110:113], v[168:171], v[200:203], v[110:113]
	v_mfma_f32_16x16x32_bf16 v[102:105], v[134:137], v[208:211], v[102:105]
	v_mfma_f32_16x16x32_bf16 v[94:97], v[168:171], v[208:211], v[94:97]
	v_mfma_f32_16x16x32_bf16 v[86:89], v[134:137], v[216:219], v[86:89]
	v_mfma_f32_16x16x32_bf16 v[78:81], v[168:171], v[216:219], v[78:81]
	v_mfma_f32_16x16x32_bf16 v[114:117], v[176:179], v[192:195], v[114:117]
	v_mfma_f32_16x16x32_bf16 v[106:109], v[184:187], v[192:195], v[106:109]
	v_mfma_f32_16x16x32_bf16 v[98:101], v[176:179], v[200:203], v[98:101]
	v_mfma_f32_16x16x32_bf16 v[90:93], v[184:187], v[200:203], v[90:93]
	v_mfma_f32_16x16x32_bf16 v[82:85], v[176:179], v[208:211], v[82:85]
	v_mfma_f32_16x16x32_bf16 v[74:77], v[184:187], v[208:211], v[74:77]
	v_mfma_f32_16x16x32_bf16 v[70:73], v[176:179], v[216:219], v[70:73]
	v_mfma_f32_16x16x32_bf16 v[66:69], v[184:187], v[216:219], v[66:69]
	s_setprio 0
	s_barrier
	s_add_i32 s96, s90, s26
	v_lshl_add_u64 v[220:221], s[82:83], 0, v[140:141]
	s_mov_b32 m0, s96
	ds_read_b128 v[188:191], v163 offset:16384
	ds_read_b128 v[192:195], v163 offset:17408
	ds_read_b128 v[196:199], v163 offset:18432
	ds_read_b128 v[200:203], v163 offset:19456
	ds_read_b128 v[204:207], v163 offset:20480
	ds_read_b128 v[208:211], v163 offset:21504
	ds_read_b128 v[212:215], v163 offset:22528
	ds_read_b128 v[216:219], v163 offset:23552
	global_load_lds_dwordx4 v[220:221], off
	s_add_i32 m0, s96, 0x2000
	s_add_u32 s96, s82, 0x40000
	v_lshl_add_u64 v[222:223], s[82:83], 0, v[144:145]
	s_addc_u32 s97, s83, 0
	s_add_i32 s98, s91, s26
	global_load_lds_dwordx4 v[222:223], off
	v_lshl_add_u64 v[224:225], s[96:97], 0, v[140:141]
	s_mov_b32 m0, s98
	v_lshl_add_u64 v[226:227], s[84:85], 0, v[142:143]
	global_load_lds_dwordx4 v[224:225], off
	v_lshl_add_u64 v[224:225], s[96:97], 0, v[144:145]
	s_add_i32 m0, s98, 0x2000
	s_nop 0
	global_load_lds_dwordx4 v[224:225], off
	v_lshl_add_u64 v[224:225], s[84:85], 0, v[138:139]
	s_mov_b32 m0, s27
	s_nop 0
	global_load_lds_dwordx4 v[224:225], off
	s_mov_b32 m0, s28
	s_nop 0
	global_load_lds_dwordx4 v[226:227], off
	s_waitcnt vmcnt(8)
	s_waitcnt lgkmcnt(0)
	s_setprio 1
	s_waitcnt lgkmcnt(0)
	s_barrier
	v_mfma_f32_16x16x32_bf16 v[62:65], v[130:133], v[188:191], 0
	v_mfma_f32_16x16x32_bf16 v[58:61], v[164:167], v[188:191], 0
	v_mfma_f32_16x16x32_bf16 v[54:57], v[130:133], v[196:199], 0
	v_mfma_f32_16x16x32_bf16 v[46:49], v[164:167], v[196:199], 0
	v_mfma_f32_16x16x32_bf16 v[38:41], v[130:133], v[204:207], 0
	v_mfma_f32_16x16x32_bf16 v[30:33], v[164:167], v[204:207], 0
	v_mfma_f32_16x16x32_bf16 v[22:25], v[130:133], v[212:215], 0
	v_mfma_f32_16x16x32_bf16 v[14:17], v[164:167], v[212:215], 0
	v_mfma_f32_16x16x32_bf16 v[50:53], v[172:175], v[188:191], 0
	v_mfma_f32_16x16x32_bf16 v[42:45], v[180:183], v[188:191], 0
	v_mfma_f32_16x16x32_bf16 v[34:37], v[172:175], v[196:199], 0
	v_mfma_f32_16x16x32_bf16 v[26:29], v[180:183], v[196:199], 0
	v_mfma_f32_16x16x32_bf16 v[18:21], v[172:175], v[204:207], 0
	v_mfma_f32_16x16x32_bf16 v[10:13], v[180:183], v[204:207], 0
	v_mfma_f32_16x16x32_bf16 v[6:9], v[172:175], v[212:215], 0
	v_mfma_f32_16x16x32_bf16 v[2:5], v[180:183], v[212:215], 0
	v_mfma_f32_16x16x32_bf16 v[62:65], v[134:137], v[192:195], v[62:65]
	v_mfma_f32_16x16x32_bf16 v[58:61], v[168:171], v[192:195], v[58:61]
	v_mfma_f32_16x16x32_bf16 v[54:57], v[134:137], v[200:203], v[54:57]
	v_mfma_f32_16x16x32_bf16 v[46:49], v[168:171], v[200:203], v[46:49]
	v_mfma_f32_16x16x32_bf16 v[38:41], v[134:137], v[208:211], v[38:41]
	v_mfma_f32_16x16x32_bf16 v[30:33], v[168:171], v[208:211], v[30:33]
	v_mfma_f32_16x16x32_bf16 v[22:25], v[134:137], v[216:219], v[22:25]
	v_mfma_f32_16x16x32_bf16 v[14:17], v[168:171], v[216:219], v[14:17]
	v_mfma_f32_16x16x32_bf16 v[50:53], v[176:179], v[192:195], v[50:53]
	v_mfma_f32_16x16x32_bf16 v[42:45], v[184:187], v[192:195], v[42:45]
	v_mfma_f32_16x16x32_bf16 v[34:37], v[176:179], v[200:203], v[34:37]
	v_mfma_f32_16x16x32_bf16 v[26:29], v[184:187], v[200:203], v[26:29]
	v_mfma_f32_16x16x32_bf16 v[18:21], v[176:179], v[208:211], v[18:21]
	v_mfma_f32_16x16x32_bf16 v[10:13], v[184:187], v[208:211], v[10:13]
	v_mfma_f32_16x16x32_bf16 v[6:9], v[176:179], v[216:219], v[6:9]
	v_mfma_f32_16x16x32_bf16 v[2:5], v[184:187], v[216:219], v[2:5]
	s_setprio 0
	s_barrier
	s_add_i32 s96, 0, 0x18000
	v_add_u32_e32 v146, s96, v160
	s_add_i32 s97, 0, 0x1c000
	ds_read_b128 v[130:133], v146
	ds_read_b128 v[134:137], v146 offset:1024
	ds_read_b128 v[164:167], v146 offset:2048
	ds_read_b128 v[168:171], v146 offset:3072
	v_add_u32_e32 v146, s97, v160
	ds_read_b128 v[172:175], v146
	ds_read_b128 v[176:179], v146 offset:1024
	ds_read_b128 v[180:183], v146 offset:2048
	ds_read_b128 v[184:187], v146 offset:3072
	s_add_u32 s84, s84, 0x40000
	s_addc_u32 s85, s85, 0
	s_mov_b32 m0, s29
	v_lshl_add_u64 v[228:229], s[84:85], 0, v[138:139]
	ds_read_b128 v[188:191], v163 offset:32768
	ds_read_b128 v[192:195], v163 offset:33792
	ds_read_b128 v[196:199], v163 offset:34816
	ds_read_b128 v[200:203], v163 offset:35840
	ds_read_b128 v[204:207], v163 offset:36864
	ds_read_b128 v[208:211], v163 offset:37888
	ds_read_b128 v[212:215], v163 offset:38912
	ds_read_b128 v[216:219], v163 offset:39936
	global_load_lds_dwordx4 v[228:229], off
	v_lshl_add_u64 v[228:229], s[84:85], 0, v[142:143]
	s_mov_b32 m0, s79
	s_nop 0
	global_load_lds_dwordx4 v[228:229], off
	s_waitcnt vmcnt(8)
	s_waitcnt lgkmcnt(0)
	s_setprio 1
	s_waitcnt lgkmcnt(0)
	s_barrier
	v_mfma_f32_16x16x32_bf16 v[126:129], v[130:133], v[188:191], v[126:129]
	v_mfma_f32_16x16x32_bf16 v[122:125], v[164:167], v[188:191], v[122:125]
	v_mfma_f32_16x16x32_bf16 v[118:121], v[130:133], v[196:199], v[118:121]
	v_mfma_f32_16x16x32_bf16 v[110:113], v[164:167], v[196:199], v[110:113]
	v_mfma_f32_16x16x32_bf16 v[102:105], v[130:133], v[204:207], v[102:105]
	v_mfma_f32_16x16x32_bf16 v[94:97], v[164:167], v[204:207], v[94:97]
	v_mfma_f32_16x16x32_bf16 v[86:89], v[130:133], v[212:215], v[86:89]
	v_mfma_f32_16x16x32_bf16 v[78:81], v[164:167], v[212:215], v[78:81]
	v_mfma_f32_16x16x32_bf16 v[114:117], v[172:175], v[188:191], v[114:117]
	v_mfma_f32_16x16x32_bf16 v[106:109], v[180:183], v[188:191], v[106:109]
	v_mfma_f32_16x16x32_bf16 v[98:101], v[172:175], v[196:199], v[98:101]
	v_mfma_f32_16x16x32_bf16 v[90:93], v[180:183], v[196:199], v[90:93]
	v_mfma_f32_16x16x32_bf16 v[82:85], v[172:175], v[204:207], v[82:85]
	v_mfma_f32_16x16x32_bf16 v[74:77], v[180:183], v[204:207], v[74:77]
	v_mfma_f32_16x16x32_bf16 v[70:73], v[172:175], v[212:215], v[70:73]
	v_mfma_f32_16x16x32_bf16 v[66:69], v[180:183], v[212:215], v[66:69]
	v_mfma_f32_16x16x32_bf16 v[126:129], v[134:137], v[192:195], v[126:129]
	v_mfma_f32_16x16x32_bf16 v[122:125], v[168:171], v[192:195], v[122:125]
	v_mfma_f32_16x16x32_bf16 v[118:121], v[134:137], v[200:203], v[118:121]
	v_mfma_f32_16x16x32_bf16 v[110:113], v[168:171], v[200:203], v[110:113]
	v_mfma_f32_16x16x32_bf16 v[102:105], v[134:137], v[208:211], v[102:105]
	v_mfma_f32_16x16x32_bf16 v[94:97], v[168:171], v[208:211], v[94:97]
	v_mfma_f32_16x16x32_bf16 v[86:89], v[134:137], v[216:219], v[86:89]
	v_mfma_f32_16x16x32_bf16 v[78:81], v[168:171], v[216:219], v[78:81]
	v_mfma_f32_16x16x32_bf16 v[114:117], v[176:179], v[192:195], v[114:117]
	v_mfma_f32_16x16x32_bf16 v[106:109], v[184:187], v[192:195], v[106:109]
	v_mfma_f32_16x16x32_bf16 v[98:101], v[176:179], v[200:203], v[98:101]
	v_mfma_f32_16x16x32_bf16 v[90:93], v[184:187], v[200:203], v[90:93]
	v_mfma_f32_16x16x32_bf16 v[82:85], v[176:179], v[208:211], v[82:85]
	v_mfma_f32_16x16x32_bf16 v[74:77], v[184:187], v[208:211], v[74:77]
	v_mfma_f32_16x16x32_bf16 v[70:73], v[176:179], v[216:219], v[70:73]
	v_mfma_f32_16x16x32_bf16 v[66:69], v[184:187], v[216:219], v[66:69]
	s_setprio 0
	s_barrier
	s_add_i32 s84, s96, s26
	v_lshl_add_u64 v[220:221], v[220:221], 0, s[40:41]
	s_mov_b32 m0, s84
	ds_read_b128 v[188:191], v163 offset:49152
	ds_read_b128 v[192:195], v163 offset:50176
	ds_read_b128 v[196:199], v163 offset:51200
	ds_read_b128 v[200:203], v163 offset:52224
	ds_read_b128 v[204:207], v163 offset:53248
	ds_read_b128 v[208:211], v163 offset:54272
	ds_read_b128 v[212:215], v163 offset:55296
	ds_read_b128 v[216:219], v163 offset:56320
	global_load_lds_dwordx4 v[220:221], off
	s_add_i32 m0, s84, 0x2000
	s_add_u32 s82, s82, 0x40080
	v_lshl_add_u64 v[220:221], v[222:223], 0, s[40:41]
	s_addc_u32 s83, s83, 0
	s_add_i32 s84, s97, s26
	global_load_lds_dwordx4 v[220:221], off
	v_lshl_add_u64 v[220:221], s[82:83], 0, v[140:141]
	s_mov_b32 m0, s84
	s_nop 0
	global_load_lds_dwordx4 v[220:221], off
	v_lshl_add_u64 v[220:221], s[82:83], 0, v[144:145]
	s_add_i32 m0, s84, 0x2000
	s_nop 0
	global_load_lds_dwordx4 v[220:221], off
	v_lshl_add_u64 v[220:221], v[224:225], 0, s[40:41]
	s_mov_b32 m0, s87
	s_nop 0
	global_load_lds_dwordx4 v[220:221], off
	v_lshl_add_u64 v[220:221], v[226:227], 0, s[40:41]
	s_mov_b32 m0, s88
	s_nop 0
	global_load_lds_dwordx4 v[220:221], off
	s_waitcnt vmcnt(8)
	s_waitcnt lgkmcnt(0)
	s_setprio 1
	s_waitcnt lgkmcnt(0)
	s_barrier
	v_mfma_f32_16x16x32_bf16 v[62:65], v[130:133], v[188:191], v[62:65]
	v_mfma_f32_16x16x32_bf16 v[58:61], v[164:167], v[188:191], v[58:61]
	v_mfma_f32_16x16x32_bf16 v[54:57], v[130:133], v[196:199], v[54:57]
	v_mfma_f32_16x16x32_bf16 v[46:49], v[164:167], v[196:199], v[46:49]
	v_mfma_f32_16x16x32_bf16 v[38:41], v[130:133], v[204:207], v[38:41]
	v_mfma_f32_16x16x32_bf16 v[30:33], v[164:167], v[204:207], v[30:33]
	v_mfma_f32_16x16x32_bf16 v[22:25], v[130:133], v[212:215], v[22:25]
	v_mfma_f32_16x16x32_bf16 v[14:17], v[164:167], v[212:215], v[14:17]
	v_mfma_f32_16x16x32_bf16 v[50:53], v[172:175], v[188:191], v[50:53]
	v_mfma_f32_16x16x32_bf16 v[42:45], v[180:183], v[188:191], v[42:45]
	v_mfma_f32_16x16x32_bf16 v[34:37], v[172:175], v[196:199], v[34:37]
	v_mfma_f32_16x16x32_bf16 v[26:29], v[180:183], v[196:199], v[26:29]
	v_mfma_f32_16x16x32_bf16 v[18:21], v[172:175], v[204:207], v[18:21]
	v_mfma_f32_16x16x32_bf16 v[10:13], v[180:183], v[204:207], v[10:13]
	v_mfma_f32_16x16x32_bf16 v[6:9], v[172:175], v[212:215], v[6:9]
	v_mfma_f32_16x16x32_bf16 v[2:5], v[180:183], v[212:215], v[2:5]
	v_mfma_f32_16x16x32_bf16 v[62:65], v[134:137], v[192:195], v[62:65]
	v_mfma_f32_16x16x32_bf16 v[58:61], v[168:171], v[192:195], v[58:61]
	v_mfma_f32_16x16x32_bf16 v[54:57], v[134:137], v[200:203], v[54:57]
	v_mfma_f32_16x16x32_bf16 v[46:49], v[168:171], v[200:203], v[46:49]
	v_mfma_f32_16x16x32_bf16 v[38:41], v[134:137], v[208:211], v[38:41]
	v_mfma_f32_16x16x32_bf16 v[30:33], v[168:171], v[208:211], v[30:33]
	v_mfma_f32_16x16x32_bf16 v[22:25], v[134:137], v[216:219], v[22:25]
	v_mfma_f32_16x16x32_bf16 v[14:17], v[168:171], v[216:219], v[14:17]
	v_mfma_f32_16x16x32_bf16 v[50:53], v[176:179], v[192:195], v[50:53]
	v_mfma_f32_16x16x32_bf16 v[42:45], v[184:187], v[192:195], v[42:45]
	v_mfma_f32_16x16x32_bf16 v[34:37], v[176:179], v[200:203], v[34:37]
	v_mfma_f32_16x16x32_bf16 v[26:29], v[184:187], v[200:203], v[26:29]
	v_mfma_f32_16x16x32_bf16 v[18:21], v[176:179], v[208:211], v[18:21]
	v_mfma_f32_16x16x32_bf16 v[10:13], v[184:187], v[208:211], v[10:13]
	v_mfma_f32_16x16x32_bf16 v[6:9], v[176:179], v[216:219], v[6:9]
	v_mfma_f32_16x16x32_bf16 v[2:5], v[184:187], v[216:219], v[2:5]
	s_setprio 0
	s_barrier
	s_add_i32 s95, s95, 2
	s_add_u32 s80, s80, 0x100
	s_addc_u32 s81, s81, 0
	s_add_u32 s93, s93, 0x100
	s_addc_u32 s94, s94, 0
	s_cmp_gt_u32 s95, 13
	s_cbranch_scc1 .Lpeel_exit_p2
.LBB0_245:
	ds_read_b128 v[130:133], v161
	ds_read_b128 v[134:137], v161 offset:1024
	ds_read_b128 v[164:167], v161 offset:2048
	ds_read_b128 v[168:171], v161 offset:3072
	ds_read_b128 v[172:175], v162
	ds_read_b128 v[176:179], v162 offset:1024
	ds_read_b128 v[180:183], v162 offset:2048
	ds_read_b128 v[184:187], v162 offset:3072
	s_add_u32 s82, s80, 0xfffc0080
	s_addc_u32 s83, s81, -1
	s_cmp_eq_u32 s95, 12
	s_cselect_b32 s85, s0, s83
	s_cselect_b32 s84, s7, s82
	s_cselect_b32 s83, s47, s94
	s_cselect_b32 s82, s73, s93
	v_lshl_add_u64 v[220:221], s[80:81], 0, v[150:151]
	s_add_i32 m0, s27, 0xc000
	ds_read_b128 v[188:191], v163
	ds_read_b128 v[192:195], v163 offset:1024
	ds_read_b128 v[196:199], v163 offset:2048
	ds_read_b128 v[200:203], v163 offset:3072
	ds_read_b128 v[204:207], v163 offset:4096
	ds_read_b128 v[208:211], v163 offset:5120
	ds_read_b128 v[212:215], v163 offset:6144
	ds_read_b128 v[216:219], v163 offset:7168
	global_load_lds_dwordx4 v[220:221], off
	v_lshl_add_u64 v[220:221], s[80:81], 0, v[152:153]
	s_add_i32 m0, s27, 0xe000
	s_nop 0
	global_load_lds_dwordx4 v[220:221], off
	s_waitcnt vmcnt(8)
	s_waitcnt lgkmcnt(0)
	s_setprio 1
	s_waitcnt lgkmcnt(0)
	s_barrier
	v_mfma_f32_16x16x32_bf16 v[126:129], v[130:133], v[188:191], v[126:129]
	v_mfma_f32_16x16x32_bf16 v[122:125], v[164:167], v[188:191], v[122:125]
	v_mfma_f32_16x16x32_bf16 v[118:121], v[130:133], v[196:199], v[118:121]
	v_mfma_f32_16x16x32_bf16 v[110:113], v[164:167], v[196:199], v[110:113]
	v_mfma_f32_16x16x32_bf16 v[102:105], v[130:133], v[204:207], v[102:105]
	v_mfma_f32_16x16x32_bf16 v[94:97], v[164:167], v[204:207], v[94:97]
	v_mfma_f32_16x16x32_bf16 v[86:89], v[130:133], v[212:215], v[86:89]
	v_mfma_f32_16x16x32_bf16 v[78:81], v[164:167], v[212:215], v[78:81]
	v_mfma_f32_16x16x32_bf16 v[114:117], v[172:175], v[188:191], v[114:117]
	v_mfma_f32_16x16x32_bf16 v[106:109], v[180:183], v[188:191], v[106:109]
	v_mfma_f32_16x16x32_bf16 v[98:101], v[172:175], v[196:199], v[98:101]
	v_mfma_f32_16x16x32_bf16 v[90:93], v[180:183], v[196:199], v[90:93]
	v_mfma_f32_16x16x32_bf16 v[82:85], v[172:175], v[204:207], v[82:85]
	v_mfma_f32_16x16x32_bf16 v[74:77], v[180:183], v[204:207], v[74:77]
	v_mfma_f32_16x16x32_bf16 v[70:73], v[172:175], v[212:215], v[70:73]
	v_mfma_f32_16x16x32_bf16 v[66:69], v[180:183], v[212:215], v[66:69]
	v_mfma_f32_16x16x32_bf16 v[126:129], v[134:137], v[192:195], v[126:129]
	v_mfma_f32_16x16x32_bf16 v[122:125], v[168:171], v[192:195], v[122:125]
	v_mfma_f32_16x16x32_bf16 v[118:121], v[134:137], v[200:203], v[118:121]
	v_mfma_f32_16x16x32_bf16 v[110:113], v[168:171], v[200:203], v[110:113]
	v_mfma_f32_16x16x32_bf16 v[102:105], v[134:137], v[208:211], v[102:105]
	v_mfma_f32_16x16x32_bf16 v[94:97], v[168:171], v[208:211], v[94:97]
	v_mfma_f32_16x16x32_bf16 v[86:89], v[134:137], v[216:219], v[86:89]
	v_mfma_f32_16x16x32_bf16 v[78:81], v[168:171], v[216:219], v[78:81]
	v_mfma_f32_16x16x32_bf16 v[114:117], v[176:179], v[192:195], v[114:117]
	v_mfma_f32_16x16x32_bf16 v[106:109], v[184:187], v[192:195], v[106:109]
	v_mfma_f32_16x16x32_bf16 v[98:101], v[176:179], v[200:203], v[98:101]
	v_mfma_f32_16x16x32_bf16 v[90:93], v[184:187], v[200:203], v[90:93]
	v_mfma_f32_16x16x32_bf16 v[82:85], v[176:179], v[208:211], v[82:85]
	v_mfma_f32_16x16x32_bf16 v[74:77], v[184:187], v[208:211], v[74:77]
	v_mfma_f32_16x16x32_bf16 v[70:73], v[176:179], v[216:219], v[70:73]
	v_mfma_f32_16x16x32_bf16 v[66:69], v[184:187], v[216:219], v[66:69]
	s_setprio 0
	s_barrier
	s_add_i32 s96, s90, s26
	v_lshl_add_u64 v[220:221], s[82:83], 0, v[140:141]
	s_mov_b32 m0, s96
	ds_read_b128 v[188:191], v163 offset:16384
	ds_read_b128 v[192:195], v163 offset:17408
	ds_read_b128 v[196:199], v163 offset:18432
	ds_read_b128 v[200:203], v163 offset:19456
	ds_read_b128 v[204:207], v163 offset:20480
	ds_read_b128 v[208:211], v163 offset:21504
	ds_read_b128 v[212:215], v163 offset:22528
	ds_read_b128 v[216:219], v163 offset:23552
	global_load_lds_dwordx4 v[220:221], off
	s_add_i32 m0, s96, 0x2000
	s_add_u32 s96, s82, 0x40000
	v_lshl_add_u64 v[222:223], s[82:83], 0, v[144:145]
	s_addc_u32 s97, s83, 0
	s_add_i32 s98, s91, s26
	global_load_lds_dwordx4 v[222:223], off
	v_lshl_add_u64 v[224:225], s[96:97], 0, v[140:141]
	s_mov_b32 m0, s98
	v_lshl_add_u64 v[226:227], s[84:85], 0, v[142:143]
	global_load_lds_dwordx4 v[224:225], off
	v_lshl_add_u64 v[224:225], s[96:97], 0, v[144:145]
	s_add_i32 m0, s98, 0x2000
	s_nop 0
	global_load_lds_dwordx4 v[224:225], off
	v_lshl_add_u64 v[224:225], s[84:85], 0, v[138:139]
	s_mov_b32 m0, s27
	s_nop 0
	global_load_lds_dwordx4 v[224:225], off
	s_mov_b32 m0, s28
	s_nop 0
	global_load_lds_dwordx4 v[226:227], off
	s_waitcnt vmcnt(8)
	s_waitcnt lgkmcnt(0)
	s_setprio 1
	s_waitcnt lgkmcnt(0)
	s_barrier
	v_mfma_f32_16x16x32_bf16 v[62:65], v[130:133], v[188:191], v[62:65]
	v_mfma_f32_16x16x32_bf16 v[58:61], v[164:167], v[188:191], v[58:61]
	v_mfma_f32_16x16x32_bf16 v[54:57], v[130:133], v[196:199], v[54:57]
	v_mfma_f32_16x16x32_bf16 v[46:49], v[164:167], v[196:199], v[46:49]
	v_mfma_f32_16x16x32_bf16 v[38:41], v[130:133], v[204:207], v[38:41]
	v_mfma_f32_16x16x32_bf16 v[30:33], v[164:167], v[204:207], v[30:33]
	v_mfma_f32_16x16x32_bf16 v[22:25], v[130:133], v[212:215], v[22:25]
	v_mfma_f32_16x16x32_bf16 v[14:17], v[164:167], v[212:215], v[14:17]
	v_mfma_f32_16x16x32_bf16 v[50:53], v[172:175], v[188:191], v[50:53]
	v_mfma_f32_16x16x32_bf16 v[42:45], v[180:183], v[188:191], v[42:45]
	v_mfma_f32_16x16x32_bf16 v[34:37], v[172:175], v[196:199], v[34:37]
	v_mfma_f32_16x16x32_bf16 v[26:29], v[180:183], v[196:199], v[26:29]
	v_mfma_f32_16x16x32_bf16 v[18:21], v[172:175], v[204:207], v[18:21]
	v_mfma_f32_16x16x32_bf16 v[10:13], v[180:183], v[204:207], v[10:13]
	v_mfma_f32_16x16x32_bf16 v[6:9], v[172:175], v[212:215], v[6:9]
	v_mfma_f32_16x16x32_bf16 v[2:5], v[180:183], v[212:215], v[2:5]
	v_mfma_f32_16x16x32_bf16 v[62:65], v[134:137], v[192:195], v[62:65]
	v_mfma_f32_16x16x32_bf16 v[58:61], v[168:171], v[192:195], v[58:61]
	v_mfma_f32_16x16x32_bf16 v[54:57], v[134:137], v[200:203], v[54:57]
	v_mfma_f32_16x16x32_bf16 v[46:49], v[168:171], v[200:203], v[46:49]
	v_mfma_f32_16x16x32_bf16 v[38:41], v[134:137], v[208:211], v[38:41]
	v_mfma_f32_16x16x32_bf16 v[30:33], v[168:171], v[208:211], v[30:33]
	v_mfma_f32_16x16x32_bf16 v[22:25], v[134:137], v[216:219], v[22:25]
	v_mfma_f32_16x16x32_bf16 v[14:17], v[168:171], v[216:219], v[14:17]
	v_mfma_f32_16x16x32_bf16 v[50:53], v[176:179], v[192:195], v[50:53]
	v_mfma_f32_16x16x32_bf16 v[42:45], v[184:187], v[192:195], v[42:45]
	v_mfma_f32_16x16x32_bf16 v[34:37], v[176:179], v[200:203], v[34:37]
	v_mfma_f32_16x16x32_bf16 v[26:29], v[184:187], v[200:203], v[26:29]
	v_mfma_f32_16x16x32_bf16 v[18:21], v[176:179], v[208:211], v[18:21]
	v_mfma_f32_16x16x32_bf16 v[10:13], v[184:187], v[208:211], v[10:13]
	v_mfma_f32_16x16x32_bf16 v[6:9], v[176:179], v[216:219], v[6:9]
	v_mfma_f32_16x16x32_bf16 v[2:5], v[184:187], v[216:219], v[2:5]
	s_setprio 0
	s_barrier
	s_add_i32 s96, 0, 0x18000
	v_add_u32_e32 v146, s96, v160
	s_add_i32 s97, 0, 0x1c000
	ds_read_b128 v[130:133], v146
	ds_read_b128 v[134:137], v146 offset:1024
	ds_read_b128 v[164:167], v146 offset:2048
	ds_read_b128 v[168:171], v146 offset:3072
	v_add_u32_e32 v146, s97, v160
	ds_read_b128 v[172:175], v146
	ds_read_b128 v[176:179], v146 offset:1024
	ds_read_b128 v[180:183], v146 offset:2048
	ds_read_b128 v[184:187], v146 offset:3072
	s_add_u32 s84, s84, 0x40000
	s_addc_u32 s85, s85, 0
	s_mov_b32 m0, s29
	v_lshl_add_u64 v[228:229], s[84:85], 0, v[138:139]
	ds_read_b128 v[188:191], v163 offset:32768
	ds_read_b128 v[192:195], v163 offset:33792
	ds_read_b128 v[196:199], v163 offset:34816
	ds_read_b128 v[200:203], v163 offset:35840
	ds_read_b128 v[204:207], v163 offset:36864
	ds_read_b128 v[208:211], v163 offset:37888
	ds_read_b128 v[212:215], v163 offset:38912
	ds_read_b128 v[216:219], v163 offset:39936
	global_load_lds_dwordx4 v[228:229], off
	v_lshl_add_u64 v[228:229], s[84:85], 0, v[142:143]
	s_mov_b32 m0, s79
	s_nop 0
	global_load_lds_dwordx4 v[228:229], off
	s_waitcnt vmcnt(8)
	s_waitcnt lgkmcnt(0)
	s_setprio 1
	s_waitcnt lgkmcnt(0)
	s_barrier
	v_mfma_f32_16x16x32_bf16 v[126:129], v[130:133], v[188:191], v[126:129]
	v_mfma_f32_16x16x32_bf16 v[122:125], v[164:167], v[188:191], v[122:125]
	v_mfma_f32_16x16x32_bf16 v[118:121], v[130:133], v[196:199], v[118:121]
	v_mfma_f32_16x16x32_bf16 v[110:113], v[164:167], v[196:199], v[110:113]
	v_mfma_f32_16x16x32_bf16 v[102:105], v[130:133], v[204:207], v[102:105]
	v_mfma_f32_16x16x32_bf16 v[94:97], v[164:167], v[204:207], v[94:97]
	v_mfma_f32_16x16x32_bf16 v[86:89], v[130:133], v[212:215], v[86:89]
	v_mfma_f32_16x16x32_bf16 v[78:81], v[164:167], v[212:215], v[78:81]
	v_mfma_f32_16x16x32_bf16 v[114:117], v[172:175], v[188:191], v[114:117]
	v_mfma_f32_16x16x32_bf16 v[106:109], v[180:183], v[188:191], v[106:109]
	v_mfma_f32_16x16x32_bf16 v[98:101], v[172:175], v[196:199], v[98:101]
	v_mfma_f32_16x16x32_bf16 v[90:93], v[180:183], v[196:199], v[90:93]
	v_mfma_f32_16x16x32_bf16 v[82:85], v[172:175], v[204:207], v[82:85]
	v_mfma_f32_16x16x32_bf16 v[74:77], v[180:183], v[204:207], v[74:77]
	v_mfma_f32_16x16x32_bf16 v[70:73], v[172:175], v[212:215], v[70:73]
	v_mfma_f32_16x16x32_bf16 v[66:69], v[180:183], v[212:215], v[66:69]
	v_mfma_f32_16x16x32_bf16 v[126:129], v[134:137], v[192:195], v[126:129]
	v_mfma_f32_16x16x32_bf16 v[122:125], v[168:171], v[192:195], v[122:125]
	v_mfma_f32_16x16x32_bf16 v[118:121], v[134:137], v[200:203], v[118:121]
	v_mfma_f32_16x16x32_bf16 v[110:113], v[168:171], v[200:203], v[110:113]
	v_mfma_f32_16x16x32_bf16 v[102:105], v[134:137], v[208:211], v[102:105]
	v_mfma_f32_16x16x32_bf16 v[94:97], v[168:171], v[208:211], v[94:97]
	v_mfma_f32_16x16x32_bf16 v[86:89], v[134:137], v[216:219], v[86:89]
	v_mfma_f32_16x16x32_bf16 v[78:81], v[168:171], v[216:219], v[78:81]
	v_mfma_f32_16x16x32_bf16 v[114:117], v[176:179], v[192:195], v[114:117]
	v_mfma_f32_16x16x32_bf16 v[106:109], v[184:187], v[192:195], v[106:109]
	v_mfma_f32_16x16x32_bf16 v[98:101], v[176:179], v[200:203], v[98:101]
	v_mfma_f32_16x16x32_bf16 v[90:93], v[184:187], v[200:203], v[90:93]
	v_mfma_f32_16x16x32_bf16 v[82:85], v[176:179], v[208:211], v[82:85]
	v_mfma_f32_16x16x32_bf16 v[74:77], v[184:187], v[208:211], v[74:77]
	v_mfma_f32_16x16x32_bf16 v[70:73], v[176:179], v[216:219], v[70:73]
	v_mfma_f32_16x16x32_bf16 v[66:69], v[184:187], v[216:219], v[66:69]
	s_setprio 0
	s_barrier
	s_add_i32 s84, s96, s26
	v_lshl_add_u64 v[220:221], v[220:221], 0, s[40:41]
	s_mov_b32 m0, s84
	ds_read_b128 v[188:191], v163 offset:49152
	ds_read_b128 v[192:195], v163 offset:50176
	ds_read_b128 v[196:199], v163 offset:51200
	ds_read_b128 v[200:203], v163 offset:52224
	ds_read_b128 v[204:207], v163 offset:53248
	ds_read_b128 v[208:211], v163 offset:54272
	ds_read_b128 v[212:215], v163 offset:55296
	ds_read_b128 v[216:219], v163 offset:56320
	global_load_lds_dwordx4 v[220:221], off
	s_add_i32 m0, s84, 0x2000
	s_add_u32 s82, s82, 0x40080
	v_lshl_add_u64 v[220:221], v[222:223], 0, s[40:41]
	s_addc_u32 s83, s83, 0
	s_add_i32 s84, s97, s26
	global_load_lds_dwordx4 v[220:221], off
	v_lshl_add_u64 v[220:221], s[82:83], 0, v[140:141]
	s_mov_b32 m0, s84
	s_nop 0
	global_load_lds_dwordx4 v[220:221], off
	v_lshl_add_u64 v[220:221], s[82:83], 0, v[144:145]
	s_add_i32 m0, s84, 0x2000
	s_nop 0
	global_load_lds_dwordx4 v[220:221], off
	v_lshl_add_u64 v[220:221], v[224:225], 0, s[40:41]
	s_mov_b32 m0, s87
	s_nop 0
	global_load_lds_dwordx4 v[220:221], off
	v_lshl_add_u64 v[220:221], v[226:227], 0, s[40:41]
	s_mov_b32 m0, s88
	s_nop 0
	global_load_lds_dwordx4 v[220:221], off
	s_waitcnt vmcnt(8)
	s_waitcnt lgkmcnt(0)
	s_setprio 1
	s_waitcnt lgkmcnt(0)
	s_barrier
	v_mfma_f32_16x16x32_bf16 v[62:65], v[130:133], v[188:191], v[62:65]
	v_mfma_f32_16x16x32_bf16 v[58:61], v[164:167], v[188:191], v[58:61]
	v_mfma_f32_16x16x32_bf16 v[54:57], v[130:133], v[196:199], v[54:57]
	v_mfma_f32_16x16x32_bf16 v[46:49], v[164:167], v[196:199], v[46:49]
	v_mfma_f32_16x16x32_bf16 v[38:41], v[130:133], v[204:207], v[38:41]
	v_mfma_f32_16x16x32_bf16 v[30:33], v[164:167], v[204:207], v[30:33]
	v_mfma_f32_16x16x32_bf16 v[22:25], v[130:133], v[212:215], v[22:25]
	v_mfma_f32_16x16x32_bf16 v[14:17], v[164:167], v[212:215], v[14:17]
	v_mfma_f32_16x16x32_bf16 v[50:53], v[172:175], v[188:191], v[50:53]
	v_mfma_f32_16x16x32_bf16 v[42:45], v[180:183], v[188:191], v[42:45]
	v_mfma_f32_16x16x32_bf16 v[34:37], v[172:175], v[196:199], v[34:37]
	v_mfma_f32_16x16x32_bf16 v[26:29], v[180:183], v[196:199], v[26:29]
	v_mfma_f32_16x16x32_bf16 v[18:21], v[172:175], v[204:207], v[18:21]
	v_mfma_f32_16x16x32_bf16 v[10:13], v[180:183], v[204:207], v[10:13]
	v_mfma_f32_16x16x32_bf16 v[6:9], v[172:175], v[212:215], v[6:9]
	v_mfma_f32_16x16x32_bf16 v[2:5], v[180:183], v[212:215], v[2:5]
	v_mfma_f32_16x16x32_bf16 v[62:65], v[134:137], v[192:195], v[62:65]
	v_mfma_f32_16x16x32_bf16 v[58:61], v[168:171], v[192:195], v[58:61]
	v_mfma_f32_16x16x32_bf16 v[54:57], v[134:137], v[200:203], v[54:57]
	v_mfma_f32_16x16x32_bf16 v[46:49], v[168:171], v[200:203], v[46:49]
	v_mfma_f32_16x16x32_bf16 v[38:41], v[134:137], v[208:211], v[38:41]
	v_mfma_f32_16x16x32_bf16 v[30:33], v[168:171], v[208:211], v[30:33]
	v_mfma_f32_16x16x32_bf16 v[22:25], v[134:137], v[216:219], v[22:25]
	v_mfma_f32_16x16x32_bf16 v[14:17], v[168:171], v[216:219], v[14:17]
	v_mfma_f32_16x16x32_bf16 v[50:53], v[176:179], v[192:195], v[50:53]
	v_mfma_f32_16x16x32_bf16 v[42:45], v[184:187], v[192:195], v[42:45]
	v_mfma_f32_16x16x32_bf16 v[34:37], v[176:179], v[200:203], v[34:37]
	v_mfma_f32_16x16x32_bf16 v[26:29], v[184:187], v[200:203], v[26:29]
	v_mfma_f32_16x16x32_bf16 v[18:21], v[176:179], v[208:211], v[18:21]
	v_mfma_f32_16x16x32_bf16 v[10:13], v[184:187], v[208:211], v[10:13]
	v_mfma_f32_16x16x32_bf16 v[6:9], v[176:179], v[216:219], v[6:9]
	v_mfma_f32_16x16x32_bf16 v[2:5], v[184:187], v[216:219], v[2:5]
	s_setprio 0
	s_barrier
	s_add_i32 s95, s95, 2
	s_add_u32 s80, s80, 0x100
	s_addc_u32 s81, s81, 0
	s_add_u32 s93, s93, 0x100
	s_addc_u32 s94, s94, 0
	s_cmp_gt_u32 s95, 13
	s_cbranch_scc0 .LBB0_245

.LBB0_567:
	v_add_u32_e32 v153, s71, v151
	ds_read_b128 v[154:157], v153
	ds_read_b128 v[158:161], v153 offset:1024
	ds_read_b128 v[162:165], v153 offset:2048
	ds_read_b128 v[166:169], v153 offset:3072
	v_add_u32_e32 v153, s72, v151
	s_add_u32 s42, s10, s40
	ds_read_b128 v[170:173], v153
	ds_read_b128 v[174:177], v153 offset:1024
	ds_read_b128 v[178:181], v153 offset:2048
	ds_read_b128 v[182:185], v153 offset:3072
	s_addc_u32 s43, s11, s41
	s_add_u32 s42, s42, 0x100
	s_addc_u32 s43, s43, 0
	s_add_u32 s76, s0, s40
	s_addc_u32 s77, s29, s41
	s_cmpk_eq_i32 s40, 0x700
	s_cselect_b32 s45, s21, s43
	s_cselect_b32 s44, s73, s42
	s_cselect_b32 s43, s19, s77
	s_cselect_b32 s42, s74, s76
	v_lshl_add_u64 v[214:215], v[146:147], 0, s[40:41]
	s_add_i32 m0, s17, 0xc000
	ds_read_b128 v[186:189], v152
	ds_read_b128 v[190:193], v152 offset:1024
	ds_read_b128 v[194:197], v152 offset:2048
	ds_read_b128 v[198:201], v152 offset:3072
	ds_read_b128 v[202:205], v152 offset:4096
	ds_read_b128 v[206:209], v152 offset:5120
	ds_read_b128 v[210:213], v152 offset:6144
	ds_read_b128 v[220:223], v152 offset:7168
	global_load_lds_dwordx4 v[214:215], off
	v_lshl_add_u64 v[214:215], v[148:149], 0, s[40:41]
	s_add_i32 m0, s17, 0xe000
	s_nop 0
	global_load_lds_dwordx4 v[214:215], off
	s_waitcnt vmcnt(8)
	s_waitcnt lgkmcnt(0)
	s_setprio 1
	s_waitcnt lgkmcnt(0)
	s_barrier
	v_mfma_f32_16x16x32_bf16 v[126:129], v[154:157], v[186:189], v[126:129]
	v_mfma_f32_16x16x32_bf16 v[122:125], v[162:165], v[186:189], v[122:125]
	v_mfma_f32_16x16x32_bf16 v[110:113], v[154:157], v[194:197], v[110:113]
	v_mfma_f32_16x16x32_bf16 v[106:109], v[162:165], v[194:197], v[106:109]
	v_mfma_f32_16x16x32_bf16 v[94:97], v[154:157], v[202:205], v[94:97]
	v_mfma_f32_16x16x32_bf16 v[90:93], v[162:165], v[202:205], v[90:93]
	v_mfma_f32_16x16x32_bf16 v[78:81], v[154:157], v[210:213], v[78:81]
	v_mfma_f32_16x16x32_bf16 v[74:77], v[162:165], v[210:213], v[74:77]
	v_mfma_f32_16x16x32_bf16 v[118:121], v[170:173], v[186:189], v[118:121]
	v_mfma_f32_16x16x32_bf16 v[114:117], v[178:181], v[186:189], v[114:117]
	v_mfma_f32_16x16x32_bf16 v[102:105], v[170:173], v[194:197], v[102:105]
	v_mfma_f32_16x16x32_bf16 v[98:101], v[178:181], v[194:197], v[98:101]
	v_mfma_f32_16x16x32_bf16 v[86:89], v[170:173], v[202:205], v[86:89]
	v_mfma_f32_16x16x32_bf16 v[82:85], v[178:181], v[202:205], v[82:85]
	v_mfma_f32_16x16x32_bf16 v[70:73], v[170:173], v[210:213], v[70:73]
	v_mfma_f32_16x16x32_bf16 v[66:69], v[178:181], v[210:213], v[66:69]
	v_mfma_f32_16x16x32_bf16 v[126:129], v[158:161], v[190:193], v[126:129]
	v_mfma_f32_16x16x32_bf16 v[122:125], v[166:169], v[190:193], v[122:125]
	v_mfma_f32_16x16x32_bf16 v[110:113], v[158:161], v[198:201], v[110:113]
	v_mfma_f32_16x16x32_bf16 v[106:109], v[166:169], v[198:201], v[106:109]
	v_mfma_f32_16x16x32_bf16 v[94:97], v[158:161], v[206:209], v[94:97]
	v_mfma_f32_16x16x32_bf16 v[90:93], v[166:169], v[206:209], v[90:93]
	v_mfma_f32_16x16x32_bf16 v[78:81], v[158:161], v[220:223], v[78:81]
	v_mfma_f32_16x16x32_bf16 v[74:77], v[166:169], v[220:223], v[74:77]
	v_mfma_f32_16x16x32_bf16 v[118:121], v[174:177], v[190:193], v[118:121]
	v_mfma_f32_16x16x32_bf16 v[114:117], v[182:185], v[190:193], v[114:117]
	v_mfma_f32_16x16x32_bf16 v[102:105], v[174:177], v[198:201], v[102:105]
	v_mfma_f32_16x16x32_bf16 v[98:101], v[182:185], v[198:201], v[98:101]
	v_mfma_f32_16x16x32_bf16 v[86:89], v[174:177], v[206:209], v[86:89]
	v_mfma_f32_16x16x32_bf16 v[82:85], v[182:185], v[206:209], v[82:85]
	v_mfma_f32_16x16x32_bf16 v[70:73], v[174:177], v[220:223], v[70:73]
	v_mfma_f32_16x16x32_bf16 v[66:69], v[182:185], v[220:223], v[66:69]
	s_setprio 0
	s_barrier
	s_add_i32 s76, s71, s49
	v_lshl_add_u64 v[214:215], s[42:43], 0, v[132:133]
	s_mov_b32 m0, s76
	ds_read_b128 v[186:189], v152 offset:16384
	ds_read_b128 v[190:193], v152 offset:17408
	ds_read_b128 v[194:197], v152 offset:18432
	ds_read_b128 v[198:201], v152 offset:19456
	ds_read_b128 v[202:205], v152 offset:20480
	ds_read_b128 v[206:209], v152 offset:21504
	ds_read_b128 v[210:213], v152 offset:22528
	ds_read_b128 v[220:223], v152 offset:23552
	global_load_lds_dwordx4 v[214:215], off
	s_add_i32 m0, s76, 0x2000
	s_add_u32 s76, s42, 0x40000
	v_lshl_add_u64 v[224:225], s[42:43], 0, v[136:137]
	s_addc_u32 s77, s43, 0
	s_add_i32 s78, s72, s49
	global_load_lds_dwordx4 v[224:225], off
	v_lshl_add_u64 v[226:227], s[76:77], 0, v[132:133]
	s_mov_b32 m0, s78
	v_lshl_add_u64 v[228:229], s[44:45], 0, v[134:135]
	global_load_lds_dwordx4 v[226:227], off
	v_lshl_add_u64 v[226:227], s[76:77], 0, v[136:137]
	s_add_i32 m0, s78, 0x2000
	s_nop 0
	global_load_lds_dwordx4 v[226:227], off
	v_lshl_add_u64 v[226:227], s[44:45], 0, v[130:131]
	s_mov_b32 m0, s17
	s_nop 0
	global_load_lds_dwordx4 v[226:227], off
	s_mov_b32 m0, s50
	s_nop 0
	global_load_lds_dwordx4 v[228:229], off
	s_waitcnt vmcnt(8)
	s_waitcnt lgkmcnt(0)
	s_setprio 1
	s_waitcnt lgkmcnt(0)
	s_barrier
	v_mfma_f32_16x16x32_bf16 v[62:65], v[154:157], v[186:189], v[62:65]
	v_mfma_f32_16x16x32_bf16 v[58:61], v[162:165], v[186:189], v[58:61]
	v_mfma_f32_16x16x32_bf16 v[46:49], v[154:157], v[194:197], v[46:49]
	v_mfma_f32_16x16x32_bf16 v[42:45], v[162:165], v[194:197], v[42:45]
	v_mfma_f32_16x16x32_bf16 v[30:33], v[154:157], v[202:205], v[30:33]
	v_mfma_f32_16x16x32_bf16 v[26:29], v[162:165], v[202:205], v[26:29]
	v_mfma_f32_16x16x32_bf16 v[14:17], v[154:157], v[210:213], v[14:17]
	v_mfma_f32_16x16x32_bf16 v[10:13], v[162:165], v[210:213], v[10:13]
	v_mfma_f32_16x16x32_bf16 v[54:57], v[170:173], v[186:189], v[54:57]
	v_mfma_f32_16x16x32_bf16 v[50:53], v[178:181], v[186:189], v[50:53]
	v_mfma_f32_16x16x32_bf16 v[38:41], v[170:173], v[194:197], v[38:41]
	v_mfma_f32_16x16x32_bf16 v[34:37], v[178:181], v[194:197], v[34:37]
	v_mfma_f32_16x16x32_bf16 v[22:25], v[170:173], v[202:205], v[22:25]
	v_mfma_f32_16x16x32_bf16 v[18:21], v[178:181], v[202:205], v[18:21]
	v_mfma_f32_16x16x32_bf16 v[6:9], v[170:173], v[210:213], v[6:9]
	v_mfma_f32_16x16x32_bf16 v[2:5], v[178:181], v[210:213], v[2:5]
	v_mfma_f32_16x16x32_bf16 v[62:65], v[158:161], v[190:193], v[62:65]
	v_mfma_f32_16x16x32_bf16 v[58:61], v[166:169], v[190:193], v[58:61]
	v_mfma_f32_16x16x32_bf16 v[46:49], v[158:161], v[198:201], v[46:49]
	v_mfma_f32_16x16x32_bf16 v[42:45], v[166:169], v[198:201], v[42:45]
	v_mfma_f32_16x16x32_bf16 v[30:33], v[158:161], v[206:209], v[30:33]
	v_mfma_f32_16x16x32_bf16 v[26:29], v[166:169], v[206:209], v[26:29]
	v_mfma_f32_16x16x32_bf16 v[14:17], v[158:161], v[220:223], v[14:17]
	v_mfma_f32_16x16x32_bf16 v[10:13], v[166:169], v[220:223], v[10:13]
	v_mfma_f32_16x16x32_bf16 v[54:57], v[174:177], v[190:193], v[54:57]
	v_mfma_f32_16x16x32_bf16 v[50:53], v[182:185], v[190:193], v[50:53]
	v_mfma_f32_16x16x32_bf16 v[38:41], v[174:177], v[198:201], v[38:41]
	v_mfma_f32_16x16x32_bf16 v[34:37], v[182:185], v[198:201], v[34:37]
	v_mfma_f32_16x16x32_bf16 v[22:25], v[174:177], v[206:209], v[22:25]
	v_mfma_f32_16x16x32_bf16 v[18:21], v[182:185], v[206:209], v[18:21]
	v_mfma_f32_16x16x32_bf16 v[6:9], v[174:177], v[220:223], v[6:9]
	v_mfma_f32_16x16x32_bf16 v[2:5], v[182:185], v[220:223], v[2:5]
	s_setprio 0
	s_barrier
	s_add_i32 s76, 0, 0x18000
	v_add_u32_e32 v153, s76, v151
	s_add_i32 s77, 0, 0x1c000
	ds_read_b128 v[154:157], v153
	ds_read_b128 v[158:161], v153 offset:1024
	ds_read_b128 v[162:165], v153 offset:2048
	ds_read_b128 v[166:169], v153 offset:3072
	v_add_u32_e32 v153, s77, v151
	ds_read_b128 v[170:173], v153
	ds_read_b128 v[174:177], v153 offset:1024
	ds_read_b128 v[178:181], v153 offset:2048
	ds_read_b128 v[182:185], v153 offset:3072
	s_add_u32 s44, s44, 0x40000
	s_addc_u32 s45, s45, 0
	s_mov_b32 m0, s51
	v_lshl_add_u64 v[230:231], s[44:45], 0, v[130:131]
	ds_read_b128 v[186:189], v152 offset:32768
	ds_read_b128 v[190:193], v152 offset:33792
	ds_read_b128 v[194:197], v152 offset:34816
	ds_read_b128 v[198:201], v152 offset:35840
	ds_read_b128 v[202:205], v152 offset:36864
	ds_read_b128 v[206:209], v152 offset:37888
	ds_read_b128 v[210:213], v152 offset:38912
	ds_read_b128 v[220:223], v152 offset:39936
	global_load_lds_dwordx4 v[230:231], off
	v_lshl_add_u64 v[230:231], s[44:45], 0, v[134:135]
	s_mov_b32 m0, s60
	s_nop 0
	global_load_lds_dwordx4 v[230:231], off
	s_waitcnt vmcnt(8)
	s_waitcnt lgkmcnt(0)
	s_setprio 1
	s_waitcnt lgkmcnt(0)
	s_barrier
	v_mfma_f32_16x16x32_bf16 v[126:129], v[154:157], v[186:189], v[126:129]
	v_mfma_f32_16x16x32_bf16 v[122:125], v[162:165], v[186:189], v[122:125]
	v_mfma_f32_16x16x32_bf16 v[110:113], v[154:157], v[194:197], v[110:113]
	v_mfma_f32_16x16x32_bf16 v[106:109], v[162:165], v[194:197], v[106:109]
	v_mfma_f32_16x16x32_bf16 v[94:97], v[154:157], v[202:205], v[94:97]
	v_mfma_f32_16x16x32_bf16 v[90:93], v[162:165], v[202:205], v[90:93]
	v_mfma_f32_16x16x32_bf16 v[78:81], v[154:157], v[210:213], v[78:81]
	v_mfma_f32_16x16x32_bf16 v[74:77], v[162:165], v[210:213], v[74:77]
	v_mfma_f32_16x16x32_bf16 v[118:121], v[170:173], v[186:189], v[118:121]
	v_mfma_f32_16x16x32_bf16 v[114:117], v[178:181], v[186:189], v[114:117]
	v_mfma_f32_16x16x32_bf16 v[102:105], v[170:173], v[194:197], v[102:105]
	v_mfma_f32_16x16x32_bf16 v[98:101], v[178:181], v[194:197], v[98:101]
	v_mfma_f32_16x16x32_bf16 v[86:89], v[170:173], v[202:205], v[86:89]
	v_mfma_f32_16x16x32_bf16 v[82:85], v[178:181], v[202:205], v[82:85]
	v_mfma_f32_16x16x32_bf16 v[70:73], v[170:173], v[210:213], v[70:73]
	v_mfma_f32_16x16x32_bf16 v[66:69], v[178:181], v[210:213], v[66:69]
	v_mfma_f32_16x16x32_bf16 v[126:129], v[158:161], v[190:193], v[126:129]
	v_mfma_f32_16x16x32_bf16 v[122:125], v[166:169], v[190:193], v[122:125]
	v_mfma_f32_16x16x32_bf16 v[110:113], v[158:161], v[198:201], v[110:113]
	v_mfma_f32_16x16x32_bf16 v[106:109], v[166:169], v[198:201], v[106:109]
	v_mfma_f32_16x16x32_bf16 v[94:97], v[158:161], v[206:209], v[94:97]
	v_mfma_f32_16x16x32_bf16 v[90:93], v[166:169], v[206:209], v[90:93]
	v_mfma_f32_16x16x32_bf16 v[78:81], v[158:161], v[220:223], v[78:81]
	v_mfma_f32_16x16x32_bf16 v[74:77], v[166:169], v[220:223], v[74:77]
	v_mfma_f32_16x16x32_bf16 v[118:121], v[174:177], v[190:193], v[118:121]
	v_mfma_f32_16x16x32_bf16 v[114:117], v[182:185], v[190:193], v[114:117]
	v_mfma_f32_16x16x32_bf16 v[102:105], v[174:177], v[198:201], v[102:105]
	v_mfma_f32_16x16x32_bf16 v[98:101], v[182:185], v[198:201], v[98:101]
	v_mfma_f32_16x16x32_bf16 v[86:89], v[174:177], v[206:209], v[86:89]
	v_mfma_f32_16x16x32_bf16 v[82:85], v[182:185], v[206:209], v[82:85]
	v_mfma_f32_16x16x32_bf16 v[70:73], v[174:177], v[220:223], v[70:73]
	v_mfma_f32_16x16x32_bf16 v[66:69], v[182:185], v[220:223], v[66:69]
	s_setprio 0
	s_barrier
	s_add_i32 s44, s76, s49
	v_lshl_add_u64 v[214:215], v[214:215], 0, s[12:13]
	s_mov_b32 m0, s44
	ds_read_b128 v[186:189], v152 offset:49152
	ds_read_b128 v[190:193], v152 offset:50176
	ds_read_b128 v[194:197], v152 offset:51200
	ds_read_b128 v[198:201], v152 offset:52224
	ds_read_b128 v[202:205], v152 offset:53248
	ds_read_b128 v[206:209], v152 offset:54272
	ds_read_b128 v[210:213], v152 offset:55296
	ds_read_b128 v[220:223], v152 offset:56320
	global_load_lds_dwordx4 v[214:215], off
	s_add_i32 m0, s44, 0x2000
	s_add_u32 s42, s42, 0x40080
	v_lshl_add_u64 v[214:215], v[224:225], 0, s[12:13]
	s_addc_u32 s43, s43, 0
	s_add_i32 s44, s77, s49
	global_load_lds_dwordx4 v[214:215], off
	v_lshl_add_u64 v[214:215], s[42:43], 0, v[132:133]
	s_mov_b32 m0, s44
	s_nop 0
	global_load_lds_dwordx4 v[214:215], off
	v_lshl_add_u64 v[214:215], s[42:43], 0, v[136:137]
	s_add_i32 m0, s44, 0x2000
	s_nop 0
	global_load_lds_dwordx4 v[214:215], off
	v_lshl_add_u64 v[214:215], v[226:227], 0, s[12:13]
	s_mov_b32 m0, s68
	s_nop 0
	global_load_lds_dwordx4 v[214:215], off
	v_lshl_add_u64 v[214:215], v[228:229], 0, s[12:13]
	s_mov_b32 m0, s69
	s_nop 0
	global_load_lds_dwordx4 v[214:215], off
	s_waitcnt vmcnt(8)
	s_waitcnt lgkmcnt(0)
	s_setprio 1
	s_waitcnt lgkmcnt(0)
	s_barrier
	v_mfma_f32_16x16x32_bf16 v[62:65], v[154:157], v[186:189], v[62:65]
	v_mfma_f32_16x16x32_bf16 v[58:61], v[162:165], v[186:189], v[58:61]
	v_mfma_f32_16x16x32_bf16 v[46:49], v[154:157], v[194:197], v[46:49]
	v_mfma_f32_16x16x32_bf16 v[42:45], v[162:165], v[194:197], v[42:45]
	v_mfma_f32_16x16x32_bf16 v[30:33], v[154:157], v[202:205], v[30:33]
	v_mfma_f32_16x16x32_bf16 v[26:29], v[162:165], v[202:205], v[26:29]
	v_mfma_f32_16x16x32_bf16 v[14:17], v[154:157], v[210:213], v[14:17]
	v_mfma_f32_16x16x32_bf16 v[10:13], v[162:165], v[210:213], v[10:13]
	v_mfma_f32_16x16x32_bf16 v[54:57], v[170:173], v[186:189], v[54:57]
	v_mfma_f32_16x16x32_bf16 v[50:53], v[178:181], v[186:189], v[50:53]
	v_mfma_f32_16x16x32_bf16 v[38:41], v[170:173], v[194:197], v[38:41]
	v_mfma_f32_16x16x32_bf16 v[34:37], v[178:181], v[194:197], v[34:37]
	v_mfma_f32_16x16x32_bf16 v[22:25], v[170:173], v[202:205], v[22:25]
	v_mfma_f32_16x16x32_bf16 v[18:21], v[178:181], v[202:205], v[18:21]
	v_mfma_f32_16x16x32_bf16 v[6:9], v[170:173], v[210:213], v[6:9]
	v_mfma_f32_16x16x32_bf16 v[2:5], v[178:181], v[210:213], v[2:5]
	v_mfma_f32_16x16x32_bf16 v[62:65], v[158:161], v[190:193], v[62:65]
	v_mfma_f32_16x16x32_bf16 v[58:61], v[166:169], v[190:193], v[58:61]
	v_mfma_f32_16x16x32_bf16 v[46:49], v[158:161], v[198:201], v[46:49]
	v_mfma_f32_16x16x32_bf16 v[42:45], v[166:169], v[198:201], v[42:45]
	v_mfma_f32_16x16x32_bf16 v[30:33], v[158:161], v[206:209], v[30:33]
	v_mfma_f32_16x16x32_bf16 v[26:29], v[166:169], v[206:209], v[26:29]
	v_mfma_f32_16x16x32_bf16 v[14:17], v[158:161], v[220:223], v[14:17]
	v_mfma_f32_16x16x32_bf16 v[10:13], v[166:169], v[220:223], v[10:13]
	v_mfma_f32_16x16x32_bf16 v[54:57], v[174:177], v[190:193], v[54:57]
	v_mfma_f32_16x16x32_bf16 v[50:53], v[182:185], v[190:193], v[50:53]
	v_mfma_f32_16x16x32_bf16 v[38:41], v[174:177], v[198:201], v[38:41]
	v_mfma_f32_16x16x32_bf16 v[34:37], v[182:185], v[198:201], v[34:37]
	v_mfma_f32_16x16x32_bf16 v[22:25], v[174:177], v[206:209], v[22:25]
	v_mfma_f32_16x16x32_bf16 v[18:21], v[182:185], v[206:209], v[18:21]
	v_mfma_f32_16x16x32_bf16 v[6:9], v[174:177], v[220:223], v[6:9]
	v_mfma_f32_16x16x32_bf16 v[2:5], v[182:185], v[220:223], v[2:5]
	s_setprio 0
	s_barrier
	s_add_i32 s75, s75, 2
	s_add_u32 s40, s40, 0x100
	s_addc_u32 s41, s41, 0
	s_cmp_gt_u32 s75, 11
	s_cbranch_scc0 .LBB0_567
	s_lshl_b32 s82, s14, 19
	s_lshl_b32 s83, s16, 9
	s_add_u32 s80, s38, s82
	s_addc_u32 s81, s39, 0
	s_add_u32 s80, s80, s83
	s_addc_u32 s81, s81, 0
	v_and_b32_e32 v232, 15, v1
	s_lshr_b32 s82, s48, 2
	s_lshl_b32 s82, s82, 6
	v_lshrrev_b32_e32 v233, 4, v1
	v_add_u32_e32 v232, s82, v232
	s_and_b32 s83, s48, 3
	v_lshlrev_b32_e32 v233, 4, v233
	s_lshl_b32 s83, s83, 6
	v_lshlrev_b32_e32 v232, 11, v232
	v_add3_u32 v232, v232, v233, s83
	v_add_u32_e32 v153, s71, v151
	ds_read_b128 v[154:157], v153
	ds_read_b128 v[158:161], v153 offset:1024
	ds_read_b128 v[162:165], v153 offset:2048
	ds_read_b128 v[166:169], v153 offset:3072
	v_add_u32_e32 v153, s72, v151
	s_add_u32 s42, s10, s40
	ds_read_b128 v[170:173], v153
	ds_read_b128 v[174:177], v153 offset:1024
	ds_read_b128 v[178:181], v153 offset:2048
	ds_read_b128 v[182:185], v153 offset:3072
	s_addc_u32 s43, s11, s41
	s_add_u32 s42, s42, 0x100
	s_addc_u32 s43, s43, 0
	s_add_u32 s76, s0, s40
	s_addc_u32 s77, s29, s41
	s_cmpk_eq_i32 s40, 0x700
	s_cselect_b32 s45, s21, s43
	s_cselect_b32 s44, s73, s42
	s_cselect_b32 s43, s19, s77
	s_cselect_b32 s42, s74, s76
	v_lshl_add_u64 v[214:215], v[146:147], 0, s[40:41]
	s_add_i32 m0, s17, 0xc000
	ds_read_b128 v[186:189], v152
	ds_read_b128 v[190:193], v152 offset:1024
	ds_read_b128 v[194:197], v152 offset:2048
	ds_read_b128 v[198:201], v152 offset:3072
	ds_read_b128 v[202:205], v152 offset:4096
	ds_read_b128 v[206:209], v152 offset:5120
	ds_read_b128 v[210:213], v152 offset:6144
	ds_read_b128 v[220:223], v152 offset:7168
	global_load_lds_dwordx4 v[214:215], off
	v_lshl_add_u64 v[214:215], v[148:149], 0, s[40:41]
	s_add_i32 m0, s17, 0xe000
	s_nop 0
	global_load_lds_dwordx4 v[214:215], off
	s_waitcnt vmcnt(8)
	s_waitcnt lgkmcnt(0)
	s_setprio 1
	s_waitcnt lgkmcnt(0)
	s_barrier
	v_mfma_f32_16x16x32_bf16 v[126:129], v[154:157], v[186:189], v[126:129]
	v_mfma_f32_16x16x32_bf16 v[122:125], v[162:165], v[186:189], v[122:125]
	v_mfma_f32_16x16x32_bf16 v[110:113], v[154:157], v[194:197], v[110:113]
	v_mfma_f32_16x16x32_bf16 v[106:109], v[162:165], v[194:197], v[106:109]
	v_mfma_f32_16x16x32_bf16 v[94:97], v[154:157], v[202:205], v[94:97]
	v_mfma_f32_16x16x32_bf16 v[90:93], v[162:165], v[202:205], v[90:93]
	v_mfma_f32_16x16x32_bf16 v[78:81], v[154:157], v[210:213], v[78:81]
	v_mfma_f32_16x16x32_bf16 v[74:77], v[162:165], v[210:213], v[74:77]
	v_mfma_f32_16x16x32_bf16 v[118:121], v[170:173], v[186:189], v[118:121]
	v_mfma_f32_16x16x32_bf16 v[114:117], v[178:181], v[186:189], v[114:117]
	v_mfma_f32_16x16x32_bf16 v[102:105], v[170:173], v[194:197], v[102:105]
	v_mfma_f32_16x16x32_bf16 v[98:101], v[178:181], v[194:197], v[98:101]
	v_mfma_f32_16x16x32_bf16 v[86:89], v[170:173], v[202:205], v[86:89]
	v_mfma_f32_16x16x32_bf16 v[82:85], v[178:181], v[202:205], v[82:85]
	v_mfma_f32_16x16x32_bf16 v[70:73], v[170:173], v[210:213], v[70:73]
	v_mfma_f32_16x16x32_bf16 v[66:69], v[178:181], v[210:213], v[66:69]
	v_mfma_f32_16x16x32_bf16 v[126:129], v[158:161], v[190:193], v[126:129]
	v_mfma_f32_16x16x32_bf16 v[122:125], v[166:169], v[190:193], v[122:125]
	v_mfma_f32_16x16x32_bf16 v[110:113], v[158:161], v[198:201], v[110:113]
	v_mfma_f32_16x16x32_bf16 v[106:109], v[166:169], v[198:201], v[106:109]
	v_mfma_f32_16x16x32_bf16 v[94:97], v[158:161], v[206:209], v[94:97]
	v_mfma_f32_16x16x32_bf16 v[90:93], v[166:169], v[206:209], v[90:93]
	v_mfma_f32_16x16x32_bf16 v[78:81], v[158:161], v[220:223], v[78:81]
	v_mfma_f32_16x16x32_bf16 v[74:77], v[166:169], v[220:223], v[74:77]
	v_mfma_f32_16x16x32_bf16 v[118:121], v[174:177], v[190:193], v[118:121]
	v_mfma_f32_16x16x32_bf16 v[114:117], v[182:185], v[190:193], v[114:117]
	v_mfma_f32_16x16x32_bf16 v[102:105], v[174:177], v[198:201], v[102:105]
	v_mfma_f32_16x16x32_bf16 v[98:101], v[182:185], v[198:201], v[98:101]
	v_mfma_f32_16x16x32_bf16 v[86:89], v[174:177], v[206:209], v[86:89]
	v_mfma_f32_16x16x32_bf16 v[82:85], v[182:185], v[206:209], v[82:85]
	v_mfma_f32_16x16x32_bf16 v[70:73], v[174:177], v[220:223], v[70:73]
	v_mfma_f32_16x16x32_bf16 v[66:69], v[182:185], v[220:223], v[66:69]
	s_setprio 0
	s_barrier
	s_add_i32 s76, s71, s49
	v_lshl_add_u64 v[214:215], s[42:43], 0, v[132:133]
	s_mov_b32 m0, s76
	ds_read_b128 v[186:189], v152 offset:16384
	ds_read_b128 v[190:193], v152 offset:17408
	ds_read_b128 v[194:197], v152 offset:18432
	ds_read_b128 v[198:201], v152 offset:19456
	ds_read_b128 v[202:205], v152 offset:20480
	ds_read_b128 v[206:209], v152 offset:21504
	ds_read_b128 v[210:213], v152 offset:22528
	ds_read_b128 v[220:223], v152 offset:23552
	s_add_u32 s84, s80, 0x0
	s_addc_u32 s85, s81, 0
	global_load_lds_dwordx4 v232, s[84:85]
	s_add_i32 m0, s76, 0x2000
	s_add_u32 s76, s42, 0x40000
	v_lshl_add_u64 v[224:225], s[42:43], 0, v[136:137]
	s_addc_u32 s77, s43, 0
	s_add_i32 s78, s72, s49
	s_add_u32 s84, s80, 0x100
	s_addc_u32 s85, s81, 0
	global_load_lds_dwordx4 v232, s[84:85]
	v_lshl_add_u64 v[226:227], s[76:77], 0, v[132:133]
	s_mov_b32 m0, s78
	v_lshl_add_u64 v[228:229], s[44:45], 0, v[134:135]
	s_add_u32 s84, s80, 0x8000
	s_addc_u32 s85, s81, 0
	global_load_lds_dwordx4 v232, s[84:85]
	v_lshl_add_u64 v[226:227], s[76:77], 0, v[136:137]
	s_add_i32 m0, s78, 0x2000
	s_nop 0
	s_add_u32 s84, s80, 0x8100
	s_addc_u32 s85, s81, 0
	global_load_lds_dwordx4 v232, s[84:85]
	v_lshl_add_u64 v[226:227], s[44:45], 0, v[130:131]
	s_mov_b32 m0, s17
	s_nop 0
	s_add_u32 s84, s80, 0x10000
	s_addc_u32 s85, s81, 0
	global_load_lds_dwordx4 v232, s[84:85]
	s_mov_b32 m0, s50
	s_nop 0
	s_add_u32 s84, s80, 0x10100
	s_addc_u32 s85, s81, 0
	global_load_lds_dwordx4 v232, s[84:85]
	s_waitcnt vmcnt(8)
	s_waitcnt lgkmcnt(0)
	s_setprio 1
	s_waitcnt lgkmcnt(0)
	s_barrier
	v_mfma_f32_16x16x32_bf16 v[62:65], v[154:157], v[186:189], v[62:65]
	v_mfma_f32_16x16x32_bf16 v[58:61], v[162:165], v[186:189], v[58:61]
	v_mfma_f32_16x16x32_bf16 v[46:49], v[154:157], v[194:197], v[46:49]
	v_mfma_f32_16x16x32_bf16 v[42:45], v[162:165], v[194:197], v[42:45]
	v_mfma_f32_16x16x32_bf16 v[30:33], v[154:157], v[202:205], v[30:33]
	v_mfma_f32_16x16x32_bf16 v[26:29], v[162:165], v[202:205], v[26:29]
	v_mfma_f32_16x16x32_bf16 v[14:17], v[154:157], v[210:213], v[14:17]
	v_mfma_f32_16x16x32_bf16 v[10:13], v[162:165], v[210:213], v[10:13]
	v_mfma_f32_16x16x32_bf16 v[54:57], v[170:173], v[186:189], v[54:57]
	v_mfma_f32_16x16x32_bf16 v[50:53], v[178:181], v[186:189], v[50:53]
	v_mfma_f32_16x16x32_bf16 v[38:41], v[170:173], v[194:197], v[38:41]
	v_mfma_f32_16x16x32_bf16 v[34:37], v[178:181], v[194:197], v[34:37]
	v_mfma_f32_16x16x32_bf16 v[22:25], v[170:173], v[202:205], v[22:25]
	v_mfma_f32_16x16x32_bf16 v[18:21], v[178:181], v[202:205], v[18:21]
	v_mfma_f32_16x16x32_bf16 v[6:9], v[170:173], v[210:213], v[6:9]
	v_mfma_f32_16x16x32_bf16 v[2:5], v[178:181], v[210:213], v[2:5]
	v_mfma_f32_16x16x32_bf16 v[62:65], v[158:161], v[190:193], v[62:65]
	v_mfma_f32_16x16x32_bf16 v[58:61], v[166:169], v[190:193], v[58:61]
	v_mfma_f32_16x16x32_bf16 v[46:49], v[158:161], v[198:201], v[46:49]
	v_mfma_f32_16x16x32_bf16 v[42:45], v[166:169], v[198:201], v[42:45]
	v_mfma_f32_16x16x32_bf16 v[30:33], v[158:161], v[206:209], v[30:33]
	v_mfma_f32_16x16x32_bf16 v[26:29], v[166:169], v[206:209], v[26:29]
	v_mfma_f32_16x16x32_bf16 v[14:17], v[158:161], v[220:223], v[14:17]
	v_mfma_f32_16x16x32_bf16 v[10:13], v[166:169], v[220:223], v[10:13]
	v_mfma_f32_16x16x32_bf16 v[54:57], v[174:177], v[190:193], v[54:57]
	v_mfma_f32_16x16x32_bf16 v[50:53], v[182:185], v[190:193], v[50:53]
	v_mfma_f32_16x16x32_bf16 v[38:41], v[174:177], v[198:201], v[38:41]
	v_mfma_f32_16x16x32_bf16 v[34:37], v[182:185], v[198:201], v[34:37]
	v_mfma_f32_16x16x32_bf16 v[22:25], v[174:177], v[206:209], v[22:25]
	v_mfma_f32_16x16x32_bf16 v[18:21], v[182:185], v[206:209], v[18:21]
	v_mfma_f32_16x16x32_bf16 v[6:9], v[174:177], v[220:223], v[6:9]
	v_mfma_f32_16x16x32_bf16 v[2:5], v[182:185], v[220:223], v[2:5]
	s_setprio 0
	s_barrier
	s_add_i32 s76, 0, 0x18000
	v_add_u32_e32 v153, s76, v151
	s_add_i32 s77, 0, 0x1c000
	ds_read_b128 v[154:157], v153
	ds_read_b128 v[158:161], v153 offset:1024
	ds_read_b128 v[162:165], v153 offset:2048
	ds_read_b128 v[166:169], v153 offset:3072
	v_add_u32_e32 v153, s77, v151
	ds_read_b128 v[170:173], v153
	ds_read_b128 v[174:177], v153 offset:1024
	ds_read_b128 v[178:181], v153 offset:2048
	ds_read_b128 v[182:185], v153 offset:3072
	s_add_u32 s44, s44, 0x40000
	s_addc_u32 s45, s45, 0
	s_mov_b32 m0, s51
	v_lshl_add_u64 v[230:231], s[44:45], 0, v[130:131]
	ds_read_b128 v[186:189], v152 offset:32768
	ds_read_b128 v[190:193], v152 offset:33792
	ds_read_b128 v[194:197], v152 offset:34816
	ds_read_b128 v[198:201], v152 offset:35840
	ds_read_b128 v[202:205], v152 offset:36864
	ds_read_b128 v[206:209], v152 offset:37888
	ds_read_b128 v[210:213], v152 offset:38912
	ds_read_b128 v[220:223], v152 offset:39936
	s_add_u32 s84, s80, 0x18000
	s_addc_u32 s85, s81, 0
	global_load_lds_dwordx4 v232, s[84:85]
	v_lshl_add_u64 v[230:231], s[44:45], 0, v[134:135]
	s_mov_b32 m0, s60
	s_nop 0
	s_add_u32 s84, s80, 0x18100
	s_addc_u32 s85, s81, 0
	global_load_lds_dwordx4 v232, s[84:85]
	s_waitcnt vmcnt(8)
	s_waitcnt lgkmcnt(0)
	s_setprio 1
	s_waitcnt lgkmcnt(0)
	s_barrier
	v_mfma_f32_16x16x32_bf16 v[126:129], v[154:157], v[186:189], v[126:129]
	v_mfma_f32_16x16x32_bf16 v[122:125], v[162:165], v[186:189], v[122:125]
	v_mfma_f32_16x16x32_bf16 v[110:113], v[154:157], v[194:197], v[110:113]
	v_mfma_f32_16x16x32_bf16 v[106:109], v[162:165], v[194:197], v[106:109]
	v_mfma_f32_16x16x32_bf16 v[94:97], v[154:157], v[202:205], v[94:97]
	v_mfma_f32_16x16x32_bf16 v[90:93], v[162:165], v[202:205], v[90:93]
	v_mfma_f32_16x16x32_bf16 v[78:81], v[154:157], v[210:213], v[78:81]
	v_mfma_f32_16x16x32_bf16 v[74:77], v[162:165], v[210:213], v[74:77]
	v_mfma_f32_16x16x32_bf16 v[118:121], v[170:173], v[186:189], v[118:121]
	v_mfma_f32_16x16x32_bf16 v[114:117], v[178:181], v[186:189], v[114:117]
	v_mfma_f32_16x16x32_bf16 v[102:105], v[170:173], v[194:197], v[102:105]
	v_mfma_f32_16x16x32_bf16 v[98:101], v[178:181], v[194:197], v[98:101]
	v_mfma_f32_16x16x32_bf16 v[86:89], v[170:173], v[202:205], v[86:89]
	v_mfma_f32_16x16x32_bf16 v[82:85], v[178:181], v[202:205], v[82:85]
	v_mfma_f32_16x16x32_bf16 v[70:73], v[170:173], v[210:213], v[70:73]
	v_mfma_f32_16x16x32_bf16 v[66:69], v[178:181], v[210:213], v[66:69]
	v_mfma_f32_16x16x32_bf16 v[126:129], v[158:161], v[190:193], v[126:129]
	v_mfma_f32_16x16x32_bf16 v[122:125], v[166:169], v[190:193], v[122:125]
	v_mfma_f32_16x16x32_bf16 v[110:113], v[158:161], v[198:201], v[110:113]
	v_mfma_f32_16x16x32_bf16 v[106:109], v[166:169], v[198:201], v[106:109]
	v_mfma_f32_16x16x32_bf16 v[94:97], v[158:161], v[206:209], v[94:97]
	v_mfma_f32_16x16x32_bf16 v[90:93], v[166:169], v[206:209], v[90:93]
	v_mfma_f32_16x16x32_bf16 v[78:81], v[158:161], v[220:223], v[78:81]
	v_mfma_f32_16x16x32_bf16 v[74:77], v[166:169], v[220:223], v[74:77]
	v_mfma_f32_16x16x32_bf16 v[118:121], v[174:177], v[190:193], v[118:121]
	v_mfma_f32_16x16x32_bf16 v[114:117], v[182:185], v[190:193], v[114:117]
	v_mfma_f32_16x16x32_bf16 v[102:105], v[174:177], v[198:201], v[102:105]
	v_mfma_f32_16x16x32_bf16 v[98:101], v[182:185], v[198:201], v[98:101]
	v_mfma_f32_16x16x32_bf16 v[86:89], v[174:177], v[206:209], v[86:89]
	v_mfma_f32_16x16x32_bf16 v[82:85], v[182:185], v[206:209], v[82:85]
	v_mfma_f32_16x16x32_bf16 v[70:73], v[174:177], v[220:223], v[70:73]
	v_mfma_f32_16x16x32_bf16 v[66:69], v[182:185], v[220:223], v[66:69]
	s_setprio 0
	s_barrier
	s_add_i32 s44, s76, s49
	v_lshl_add_u64 v[214:215], v[214:215], 0, s[12:13]
	s_mov_b32 m0, s44
	ds_read_b128 v[186:189], v152 offset:49152
	ds_read_b128 v[190:193], v152 offset:50176
	ds_read_b128 v[194:197], v152 offset:51200
	ds_read_b128 v[198:201], v152 offset:52224
	ds_read_b128 v[202:205], v152 offset:53248
	ds_read_b128 v[206:209], v152 offset:54272
	ds_read_b128 v[210:213], v152 offset:55296
	ds_read_b128 v[220:223], v152 offset:56320
	s_add_u32 s84, s80, 0x40000
	s_addc_u32 s85, s81, 0
	global_load_lds_dwordx4 v232, s[84:85]
	s_add_i32 m0, s44, 0x2000
	s_add_u32 s42, s42, 0x40080
	v_lshl_add_u64 v[214:215], v[224:225], 0, s[12:13]
	s_addc_u32 s43, s43, 0
	s_add_i32 s44, s77, s49
	s_add_u32 s84, s80, 0x40100
	s_addc_u32 s85, s81, 0
	global_load_lds_dwordx4 v232, s[84:85]
	v_lshl_add_u64 v[214:215], s[42:43], 0, v[132:133]
	s_mov_b32 m0, s44
	s_nop 0
	s_add_u32 s84, s80, 0x48000
	s_addc_u32 s85, s81, 0
	global_load_lds_dwordx4 v232, s[84:85]
	v_lshl_add_u64 v[214:215], s[42:43], 0, v[136:137]
	s_add_i32 m0, s44, 0x2000
	s_nop 0
	s_add_u32 s84, s80, 0x48100
	s_addc_u32 s85, s81, 0
	global_load_lds_dwordx4 v232, s[84:85]
	v_lshl_add_u64 v[214:215], v[226:227], 0, s[12:13]
	s_mov_b32 m0, s68
	s_nop 0
	s_add_u32 s84, s80, 0x50000
	s_addc_u32 s85, s81, 0
	global_load_lds_dwordx4 v232, s[84:85]
	v_lshl_add_u64 v[214:215], v[228:229], 0, s[12:13]
	s_mov_b32 m0, s69
	s_nop 0
	s_add_u32 s84, s80, 0x50100
	s_addc_u32 s85, s81, 0
	global_load_lds_dwordx4 v232, s[84:85]
	s_waitcnt vmcnt(8)
	s_waitcnt lgkmcnt(0)
	s_setprio 1
	s_waitcnt lgkmcnt(0)
	s_barrier
	v_mfma_f32_16x16x32_bf16 v[62:65], v[154:157], v[186:189], v[62:65]
	v_mfma_f32_16x16x32_bf16 v[58:61], v[162:165], v[186:189], v[58:61]
	v_mfma_f32_16x16x32_bf16 v[46:49], v[154:157], v[194:197], v[46:49]
	v_mfma_f32_16x16x32_bf16 v[42:45], v[162:165], v[194:197], v[42:45]
	v_mfma_f32_16x16x32_bf16 v[30:33], v[154:157], v[202:205], v[30:33]
	v_mfma_f32_16x16x32_bf16 v[26:29], v[162:165], v[202:205], v[26:29]
	v_mfma_f32_16x16x32_bf16 v[14:17], v[154:157], v[210:213], v[14:17]
	v_mfma_f32_16x16x32_bf16 v[10:13], v[162:165], v[210:213], v[10:13]
	v_mfma_f32_16x16x32_bf16 v[54:57], v[170:173], v[186:189], v[54:57]
	v_mfma_f32_16x16x32_bf16 v[50:53], v[178:181], v[186:189], v[50:53]
	v_mfma_f32_16x16x32_bf16 v[38:41], v[170:173], v[194:197], v[38:41]
	v_mfma_f32_16x16x32_bf16 v[34:37], v[178:181], v[194:197], v[34:37]
	v_mfma_f32_16x16x32_bf16 v[22:25], v[170:173], v[202:205], v[22:25]
	v_mfma_f32_16x16x32_bf16 v[18:21], v[178:181], v[202:205], v[18:21]
	v_mfma_f32_16x16x32_bf16 v[6:9], v[170:173], v[210:213], v[6:9]
	v_mfma_f32_16x16x32_bf16 v[2:5], v[178:181], v[210:213], v[2:5]
	v_mfma_f32_16x16x32_bf16 v[62:65], v[158:161], v[190:193], v[62:65]
	v_mfma_f32_16x16x32_bf16 v[58:61], v[166:169], v[190:193], v[58:61]
	v_mfma_f32_16x16x32_bf16 v[46:49], v[158:161], v[198:201], v[46:49]
	v_mfma_f32_16x16x32_bf16 v[42:45], v[166:169], v[198:201], v[42:45]
	v_mfma_f32_16x16x32_bf16 v[30:33], v[158:161], v[206:209], v[30:33]
	v_mfma_f32_16x16x32_bf16 v[26:29], v[166:169], v[206:209], v[26:29]
	v_mfma_f32_16x16x32_bf16 v[14:17], v[158:161], v[220:223], v[14:17]
	v_mfma_f32_16x16x32_bf16 v[10:13], v[166:169], v[220:223], v[10:13]
	v_mfma_f32_16x16x32_bf16 v[54:57], v[174:177], v[190:193], v[54:57]
	v_mfma_f32_16x16x32_bf16 v[50:53], v[182:185], v[190:193], v[50:53]
	v_mfma_f32_16x16x32_bf16 v[38:41], v[174:177], v[198:201], v[38:41]
	v_mfma_f32_16x16x32_bf16 v[34:37], v[182:185], v[198:201], v[34:37]
	v_mfma_f32_16x16x32_bf16 v[22:25], v[174:177], v[206:209], v[22:25]
	v_mfma_f32_16x16x32_bf16 v[18:21], v[182:185], v[206:209], v[18:21]
	v_mfma_f32_16x16x32_bf16 v[6:9], v[174:177], v[220:223], v[6:9]
	v_mfma_f32_16x16x32_bf16 v[2:5], v[182:185], v[220:223], v[2:5]
	s_setprio 0
	s_barrier
	s_add_i32 s75, s75, 2
	s_add_u32 s40, s40, 0x100
	s_addc_u32 s41, s41, 0
	s_add_u32 s40, s0, 0xffffff00
	s_addc_u32 s41, s29, -1
	s_andn2_b64 vcc, exec, s[8:9]
	s_cbranch_vccnz .LBB0_570
	v_mov_b32_e32 v2, 0
	s_mov_b32 s16, s18
	s_mov_b32 s14, s20
	s_mov_b64 s[10:11], s[36:37]
	s_mov_b32 s70, s28
	v_mov_b32_e32 v3, v2
	v_mov_b32_e32 v4, v2
	v_mov_b32_e32 v5, v2
	v_mov_b32_e32 v6, v2
	v_mov_b32_e32 v7, v2
	v_mov_b32_e32 v8, v2
	v_mov_b32_e32 v9, v2
	v_mov_b32_e32 v18, v2
	v_mov_b32_e32 v19, v2
	v_mov_b32_e32 v20, v2
	v_mov_b32_e32 v21, v2
	v_mov_b32_e32 v22, v2
	v_mov_b32_e32 v23, v2
	v_mov_b32_e32 v24, v2
	v_mov_b32_e32 v25, v2
	v_mov_b32_e32 v34, v2
	v_mov_b32_e32 v35, v2
	v_mov_b32_e32 v36, v2
	v_mov_b32_e32 v37, v2
	v_mov_b32_e32 v38, v2
	v_mov_b32_e32 v39, v2
	v_mov_b32_e32 v40, v2
	v_mov_b32_e32 v41, v2
	v_mov_b32_e32 v50, v2
	v_mov_b32_e32 v51, v2
	v_mov_b32_e32 v52, v2
	v_mov_b32_e32 v53, v2
	v_mov_b32_e32 v54, v2
	v_mov_b32_e32 v55, v2
	v_mov_b32_e32 v56, v2
	v_mov_b32_e32 v57, v2
	v_mov_b32_e32 v10, v2
	v_mov_b32_e32 v11, v2
	v_mov_b32_e32 v12, v2
	v_mov_b32_e32 v13, v2
	v_mov_b32_e32 v14, v2
	v_mov_b32_e32 v15, v2
	v_mov_b32_e32 v16, v2
	v_mov_b32_e32 v17, v2
	v_mov_b32_e32 v26, v2
	v_mov_b32_e32 v27, v2
	v_mov_b32_e32 v28, v2
	v_mov_b32_e32 v29, v2
	v_mov_b32_e32 v30, v2
	v_mov_b32_e32 v31, v2
	v_mov_b32_e32 v32, v2
	v_mov_b32_e32 v33, v2
	v_mov_b32_e32 v42, v2
	v_mov_b32_e32 v43, v2
	v_mov_b32_e32 v44, v2
	v_mov_b32_e32 v45, v2
	v_mov_b32_e32 v46, v2
	v_mov_b32_e32 v47, v2
	v_mov_b32_e32 v48, v2
	v_mov_b32_e32 v49, v2
	v_mov_b32_e32 v58, v2
	v_mov_b32_e32 v59, v2
	v_mov_b32_e32 v60, v2
	v_mov_b32_e32 v61, v2
	v_mov_b32_e32 v62, v2
	v_mov_b32_e32 v63, v2
	v_mov_b32_e32 v64, v2
	v_mov_b32_e32 v65, v2
	v_mov_b32_e32 v66, v2
	v_mov_b32_e32 v67, v2
	v_mov_b32_e32 v68, v2
	v_mov_b32_e32 v69, v2
	v_mov_b32_e32 v70, v2
	v_mov_b32_e32 v71, v2
	v_mov_b32_e32 v72, v2
	v_mov_b32_e32 v73, v2
	v_mov_b32_e32 v82, v2
	v_mov_b32_e32 v83, v2
	v_mov_b32_e32 v84, v2
	v_mov_b32_e32 v85, v2
	v_mov_b32_e32 v86, v2
	v_mov_b32_e32 v87, v2
	v_mov_b32_e32 v88, v2
	v_mov_b32_e32 v89, v2
	v_mov_b32_e32 v98, v2
	v_mov_b32_e32 v99, v2
	v_mov_b32_e32 v100, v2
	v_mov_b32_e32 v101, v2
	v_mov_b32_e32 v102, v2
	v_mov_b32_e32 v103, v2
	v_mov_b32_e32 v104, v2
	v_mov_b32_e32 v105, v2
	v_mov_b32_e32 v114, v2
	v_mov_b32_e32 v115, v2
	v_mov_b32_e32 v116, v2
	v_mov_b32_e32 v117, v2
	v_mov_b32_e32 v118, v2
	v_mov_b32_e32 v119, v2
	v_mov_b32_e32 v120, v2
	v_mov_b32_e32 v121, v2
	v_mov_b32_e32 v74, v2
	v_mov_b32_e32 v75, v2
	v_mov_b32_e32 v76, v2
	v_mov_b32_e32 v77, v2
	v_mov_b32_e32 v78, v2
	v_mov_b32_e32 v79, v2
	v_mov_b32_e32 v80, v2
	v_mov_b32_e32 v81, v2
	v_mov_b32_e32 v90, v2
	v_mov_b32_e32 v91, v2
	v_mov_b32_e32 v92, v2
	v_mov_b32_e32 v93, v2
	v_mov_b32_e32 v94, v2
	v_mov_b32_e32 v95, v2
	v_mov_b32_e32 v96, v2
	v_mov_b32_e32 v97, v2
	v_mov_b32_e32 v106, v2
	v_mov_b32_e32 v107, v2
	v_mov_b32_e32 v108, v2
	v_mov_b32_e32 v109, v2
	v_mov_b32_e32 v110, v2
	v_mov_b32_e32 v111, v2
	v_mov_b32_e32 v112, v2
	v_mov_b32_e32 v113, v2
	v_mov_b32_e32 v122, v2
	v_mov_b32_e32 v123, v2
	v_mov_b32_e32 v124, v2
	v_mov_b32_e32 v125, v2
	v_mov_b32_e32 v126, v2
	v_mov_b32_e32 v127, v2
	v_mov_b32_e32 v128, v2
	v_mov_b32_e32 v129, v2
	s_andn2_b64 vcc, exec, s[6:7]
	s_cbranch_vccnz .LBB0_571
	s_branch .LBB0_572

.LBB0_767:
	s_ashr_i32 s19, s18, 31
	s_lshl_b64 s[20:21], s[18:19], 19
	s_add_u32 s20, s24, s20
	s_addc_u32 s21, s25, s21
	s_and_b64 s[26:27], s[6:7], exec
	s_cselect_b32 s0, s21, s39
	s_cselect_b32 s19, s20, s38
	s_ashr_i32 s17, s16, 31
	s_lshl_b64 s[26:27], s[16:17], 19
	s_add_u32 s26, s64, s26
	s_addc_u32 s27, s65, s27
	s_and_b64 s[42:43], s[6:7], exec
	s_cselect_b32 s17, s27, s41
	s_cselect_b32 s66, s26, s40
	s_add_u32 s38, s38, 0x40080
	s_addc_u32 s39, s39, 0
	s_add_u32 s67, s40, 0x100
	s_addc_u32 s68, s41, 0
	s_mov_b32 s69, -2
	ds_read_b128 v[146:149], v153
	ds_read_b128 v[156:159], v153 offset:1024
	ds_read_b128 v[160:163], v153 offset:2048
	ds_read_b128 v[164:167], v153 offset:3072
	ds_read_b128 v[168:171], v154
	ds_read_b128 v[172:175], v154 offset:1024
	ds_read_b128 v[176:179], v154 offset:2048
	ds_read_b128 v[180:183], v154 offset:3072
	s_add_u32 s40, s38, 0xfffc0080
	s_addc_u32 s41, s39, -1
	s_cmp_eq_u32 s69, 12
	s_cselect_b32 s43, s0, s41
	s_cselect_b32 s42, s19, s40
	s_cselect_b32 s41, s17, s68
	s_cselect_b32 s40, s66, s67
	v_lshl_add_u64 v[216:217], s[38:39], 0, v[138:139]
	s_add_i32 m0, s29, 0xc000
	ds_read_b128 v[184:187], v155
	ds_read_b128 v[188:191], v155 offset:1024
	ds_read_b128 v[192:195], v155 offset:2048
	ds_read_b128 v[196:199], v155 offset:3072
	ds_read_b128 v[200:203], v155 offset:4096
	ds_read_b128 v[204:207], v155 offset:5120
	ds_read_b128 v[208:211], v155 offset:6144
	ds_read_b128 v[212:215], v155 offset:7168
	global_load_lds_dwordx4 v[216:217], off
	v_lshl_add_u64 v[216:217], s[38:39], 0, v[140:141]
	s_add_i32 m0, s29, 0xe000
	s_nop 0
	global_load_lds_dwordx4 v[216:217], off
	s_waitcnt vmcnt(8)
	s_waitcnt lgkmcnt(0)
	s_setprio 1
	s_waitcnt lgkmcnt(0)
	s_barrier
	v_mfma_f32_16x16x32_bf16 v[126:129], v[146:149], v[184:187], 0
	v_mfma_f32_16x16x32_bf16 v[122:125], v[160:163], v[184:187], 0
	v_mfma_f32_16x16x32_bf16 v[110:113], v[146:149], v[192:195], 0
	v_mfma_f32_16x16x32_bf16 v[106:109], v[160:163], v[192:195], 0
	v_mfma_f32_16x16x32_bf16 v[94:97], v[146:149], v[200:203], 0
	v_mfma_f32_16x16x32_bf16 v[90:93], v[160:163], v[200:203], 0
	v_mfma_f32_16x16x32_bf16 v[78:81], v[146:149], v[208:211], 0
	v_mfma_f32_16x16x32_bf16 v[74:77], v[160:163], v[208:211], 0
	v_mfma_f32_16x16x32_bf16 v[118:121], v[168:171], v[184:187], 0
	v_mfma_f32_16x16x32_bf16 v[114:117], v[176:179], v[184:187], 0
	v_mfma_f32_16x16x32_bf16 v[102:105], v[168:171], v[192:195], 0
	v_mfma_f32_16x16x32_bf16 v[98:101], v[176:179], v[192:195], 0
	v_mfma_f32_16x16x32_bf16 v[86:89], v[168:171], v[200:203], 0
	v_mfma_f32_16x16x32_bf16 v[82:85], v[176:179], v[200:203], 0
	v_mfma_f32_16x16x32_bf16 v[70:73], v[168:171], v[208:211], 0
	v_mfma_f32_16x16x32_bf16 v[66:69], v[176:179], v[208:211], 0
	v_mfma_f32_16x16x32_bf16 v[126:129], v[156:159], v[188:191], v[126:129]
	v_mfma_f32_16x16x32_bf16 v[122:125], v[164:167], v[188:191], v[122:125]
	v_mfma_f32_16x16x32_bf16 v[110:113], v[156:159], v[196:199], v[110:113]
	v_mfma_f32_16x16x32_bf16 v[106:109], v[164:167], v[196:199], v[106:109]
	v_mfma_f32_16x16x32_bf16 v[94:97], v[156:159], v[204:207], v[94:97]
	v_mfma_f32_16x16x32_bf16 v[90:93], v[164:167], v[204:207], v[90:93]
	v_mfma_f32_16x16x32_bf16 v[78:81], v[156:159], v[212:215], v[78:81]
	v_mfma_f32_16x16x32_bf16 v[74:77], v[164:167], v[212:215], v[74:77]
	v_mfma_f32_16x16x32_bf16 v[118:121], v[172:175], v[188:191], v[118:121]
	v_mfma_f32_16x16x32_bf16 v[114:117], v[180:183], v[188:191], v[114:117]
	v_mfma_f32_16x16x32_bf16 v[102:105], v[172:175], v[196:199], v[102:105]
	v_mfma_f32_16x16x32_bf16 v[98:101], v[180:183], v[196:199], v[98:101]
	v_mfma_f32_16x16x32_bf16 v[86:89], v[172:175], v[204:207], v[86:89]
	v_mfma_f32_16x16x32_bf16 v[82:85], v[180:183], v[204:207], v[82:85]
	v_mfma_f32_16x16x32_bf16 v[70:73], v[172:175], v[212:215], v[70:73]
	v_mfma_f32_16x16x32_bf16 v[66:69], v[180:183], v[212:215], v[66:69]
	s_setprio 0
	s_barrier
	s_add_i32 s70, s51, s1
	v_lshl_add_u64 v[216:217], s[40:41], 0, v[134:135]
	s_mov_b32 m0, s70
	ds_read_b128 v[184:187], v155 offset:16384
	ds_read_b128 v[188:191], v155 offset:17408
	ds_read_b128 v[192:195], v155 offset:18432
	ds_read_b128 v[196:199], v155 offset:19456
	ds_read_b128 v[200:203], v155 offset:20480
	ds_read_b128 v[204:207], v155 offset:21504
	ds_read_b128 v[208:211], v155 offset:22528
	ds_read_b128 v[212:215], v155 offset:23552
	global_load_lds_dwordx4 v[216:217], off
	s_add_i32 m0, s70, 0x2000
	s_add_u32 s70, s40, 0x40000
	v_lshl_add_u64 v[218:219], s[40:41], 0, v[130:131]
	s_addc_u32 s71, s41, 0
	s_add_i32 s72, s60, s1
	global_load_lds_dwordx4 v[218:219], off
	v_lshl_add_u64 v[220:221], s[70:71], 0, v[134:135]
	s_mov_b32 m0, s72
	v_lshl_add_u64 v[222:223], s[42:43], 0, v[132:133]
	global_load_lds_dwordx4 v[220:221], off
	v_lshl_add_u64 v[220:221], s[70:71], 0, v[130:131]
	s_add_i32 m0, s72, 0x2000
	s_nop 0
	global_load_lds_dwordx4 v[220:221], off
	v_lshl_add_u64 v[220:221], s[42:43], 0, v[136:137]
	s_mov_b32 m0, s29
	s_nop 0
	global_load_lds_dwordx4 v[220:221], off
	s_mov_b32 m0, s37
	s_nop 0
	global_load_lds_dwordx4 v[222:223], off
	s_waitcnt vmcnt(8)
	s_waitcnt lgkmcnt(0)
	s_setprio 1
	s_waitcnt lgkmcnt(0)
	s_barrier
	v_mfma_f32_16x16x32_bf16 v[62:65], v[146:149], v[184:187], 0
	v_mfma_f32_16x16x32_bf16 v[58:61], v[160:163], v[184:187], 0
	v_mfma_f32_16x16x32_bf16 v[46:49], v[146:149], v[192:195], 0
	v_mfma_f32_16x16x32_bf16 v[42:45], v[160:163], v[192:195], 0
	v_mfma_f32_16x16x32_bf16 v[30:33], v[146:149], v[200:203], 0
	v_mfma_f32_16x16x32_bf16 v[26:29], v[160:163], v[200:203], 0
	v_mfma_f32_16x16x32_bf16 v[14:17], v[146:149], v[208:211], 0
	v_mfma_f32_16x16x32_bf16 v[10:13], v[160:163], v[208:211], 0
	v_mfma_f32_16x16x32_bf16 v[54:57], v[168:171], v[184:187], 0
	v_mfma_f32_16x16x32_bf16 v[50:53], v[176:179], v[184:187], 0
	v_mfma_f32_16x16x32_bf16 v[38:41], v[168:171], v[192:195], 0
	v_mfma_f32_16x16x32_bf16 v[34:37], v[176:179], v[192:195], 0
	v_mfma_f32_16x16x32_bf16 v[22:25], v[168:171], v[200:203], 0
	v_mfma_f32_16x16x32_bf16 v[18:21], v[176:179], v[200:203], 0
	v_mfma_f32_16x16x32_bf16 v[6:9], v[168:171], v[208:211], 0
	v_mfma_f32_16x16x32_bf16 v[2:5], v[176:179], v[208:211], 0
	v_mfma_f32_16x16x32_bf16 v[62:65], v[156:159], v[188:191], v[62:65]
	v_mfma_f32_16x16x32_bf16 v[58:61], v[164:167], v[188:191], v[58:61]
	v_mfma_f32_16x16x32_bf16 v[46:49], v[156:159], v[196:199], v[46:49]
	v_mfma_f32_16x16x32_bf16 v[42:45], v[164:167], v[196:199], v[42:45]
	v_mfma_f32_16x16x32_bf16 v[30:33], v[156:159], v[204:207], v[30:33]
	v_mfma_f32_16x16x32_bf16 v[26:29], v[164:167], v[204:207], v[26:29]
	v_mfma_f32_16x16x32_bf16 v[14:17], v[156:159], v[212:215], v[14:17]
	v_mfma_f32_16x16x32_bf16 v[10:13], v[164:167], v[212:215], v[10:13]
	v_mfma_f32_16x16x32_bf16 v[54:57], v[172:175], v[188:191], v[54:57]
	v_mfma_f32_16x16x32_bf16 v[50:53], v[180:183], v[188:191], v[50:53]
	v_mfma_f32_16x16x32_bf16 v[38:41], v[172:175], v[196:199], v[38:41]
	v_mfma_f32_16x16x32_bf16 v[34:37], v[180:183], v[196:199], v[34:37]
	v_mfma_f32_16x16x32_bf16 v[22:25], v[172:175], v[204:207], v[22:25]
	v_mfma_f32_16x16x32_bf16 v[18:21], v[180:183], v[204:207], v[18:21]
	v_mfma_f32_16x16x32_bf16 v[6:9], v[172:175], v[212:215], v[6:9]
	v_mfma_f32_16x16x32_bf16 v[2:5], v[180:183], v[212:215], v[2:5]
	s_setprio 0
	s_barrier
	s_add_i32 s70, 0, 0x18000
	s_add_i32 s71, 0, 0x1c000
	v_add_u32_e32 v164, s70, v151
	v_add_u32_e32 v180, s71, v151
	ds_read_b128 v[146:149], v164
	ds_read_b128 v[156:159], v164 offset:1024
	ds_read_b128 v[160:163], v164 offset:2048
	ds_read_b128 v[164:167], v164 offset:3072
	ds_read_b128 v[168:171], v180
	ds_read_b128 v[172:175], v180 offset:1024
	ds_read_b128 v[176:179], v180 offset:2048
	ds_read_b128 v[180:183], v180 offset:3072
	s_add_u32 s42, s42, 0x40000
	s_addc_u32 s43, s43, 0
	s_mov_b32 m0, s45
	v_lshl_add_u64 v[224:225], s[42:43], 0, v[136:137]
	ds_read_b128 v[184:187], v155 offset:32768
	ds_read_b128 v[188:191], v155 offset:33792
	ds_read_b128 v[192:195], v155 offset:34816
	ds_read_b128 v[196:199], v155 offset:35840
	ds_read_b128 v[200:203], v155 offset:36864
	ds_read_b128 v[204:207], v155 offset:37888
	ds_read_b128 v[208:211], v155 offset:38912
	ds_read_b128 v[212:215], v155 offset:39936
	global_load_lds_dwordx4 v[224:225], off
	v_lshl_add_u64 v[224:225], s[42:43], 0, v[132:133]
	s_mov_b32 m0, s46
	s_nop 0
	global_load_lds_dwordx4 v[224:225], off
	s_waitcnt vmcnt(8)
	s_waitcnt lgkmcnt(0)
	s_setprio 1
	s_waitcnt lgkmcnt(0)
	s_barrier
	v_mfma_f32_16x16x32_bf16 v[126:129], v[146:149], v[184:187], v[126:129]
	v_mfma_f32_16x16x32_bf16 v[122:125], v[160:163], v[184:187], v[122:125]
	v_mfma_f32_16x16x32_bf16 v[110:113], v[146:149], v[192:195], v[110:113]
	v_mfma_f32_16x16x32_bf16 v[106:109], v[160:163], v[192:195], v[106:109]
	v_mfma_f32_16x16x32_bf16 v[94:97], v[146:149], v[200:203], v[94:97]
	v_mfma_f32_16x16x32_bf16 v[90:93], v[160:163], v[200:203], v[90:93]
	v_mfma_f32_16x16x32_bf16 v[78:81], v[146:149], v[208:211], v[78:81]
	v_mfma_f32_16x16x32_bf16 v[74:77], v[160:163], v[208:211], v[74:77]
	v_mfma_f32_16x16x32_bf16 v[118:121], v[168:171], v[184:187], v[118:121]
	v_mfma_f32_16x16x32_bf16 v[114:117], v[176:179], v[184:187], v[114:117]
	v_mfma_f32_16x16x32_bf16 v[102:105], v[168:171], v[192:195], v[102:105]
	v_mfma_f32_16x16x32_bf16 v[98:101], v[176:179], v[192:195], v[98:101]
	v_mfma_f32_16x16x32_bf16 v[86:89], v[168:171], v[200:203], v[86:89]
	v_mfma_f32_16x16x32_bf16 v[82:85], v[176:179], v[200:203], v[82:85]
	v_mfma_f32_16x16x32_bf16 v[70:73], v[168:171], v[208:211], v[70:73]
	v_mfma_f32_16x16x32_bf16 v[66:69], v[176:179], v[208:211], v[66:69]
	v_mfma_f32_16x16x32_bf16 v[126:129], v[156:159], v[188:191], v[126:129]
	v_mfma_f32_16x16x32_bf16 v[122:125], v[164:167], v[188:191], v[122:125]
	v_mfma_f32_16x16x32_bf16 v[110:113], v[156:159], v[196:199], v[110:113]
	v_mfma_f32_16x16x32_bf16 v[106:109], v[164:167], v[196:199], v[106:109]
	v_mfma_f32_16x16x32_bf16 v[94:97], v[156:159], v[204:207], v[94:97]
	v_mfma_f32_16x16x32_bf16 v[90:93], v[164:167], v[204:207], v[90:93]
	v_mfma_f32_16x16x32_bf16 v[78:81], v[156:159], v[212:215], v[78:81]
	v_mfma_f32_16x16x32_bf16 v[74:77], v[164:167], v[212:215], v[74:77]
	v_mfma_f32_16x16x32_bf16 v[118:121], v[172:175], v[188:191], v[118:121]
	v_mfma_f32_16x16x32_bf16 v[114:117], v[180:183], v[188:191], v[114:117]
	v_mfma_f32_16x16x32_bf16 v[102:105], v[172:175], v[196:199], v[102:105]
	v_mfma_f32_16x16x32_bf16 v[98:101], v[180:183], v[196:199], v[98:101]
	v_mfma_f32_16x16x32_bf16 v[86:89], v[172:175], v[204:207], v[86:89]
	v_mfma_f32_16x16x32_bf16 v[82:85], v[180:183], v[204:207], v[82:85]
	v_mfma_f32_16x16x32_bf16 v[70:73], v[172:175], v[212:215], v[70:73]
	v_mfma_f32_16x16x32_bf16 v[66:69], v[180:183], v[212:215], v[66:69]
	s_setprio 0
	s_barrier
	s_add_i32 s42, s70, s1
	v_lshl_add_u64 v[216:217], v[216:217], 0, s[12:13]
	s_mov_b32 m0, s42
	ds_read_b128 v[184:187], v155 offset:49152
	ds_read_b128 v[188:191], v155 offset:50176
	ds_read_b128 v[192:195], v155 offset:51200
	ds_read_b128 v[196:199], v155 offset:52224
	ds_read_b128 v[200:203], v155 offset:53248
	ds_read_b128 v[204:207], v155 offset:54272
	ds_read_b128 v[208:211], v155 offset:55296
	ds_read_b128 v[212:215], v155 offset:56320
	global_load_lds_dwordx4 v[216:217], off
	s_add_i32 m0, s42, 0x2000
	s_add_u32 s40, s40, 0x40080
	v_lshl_add_u64 v[216:217], v[218:219], 0, s[12:13]
	s_addc_u32 s41, s41, 0
	s_add_i32 s42, s71, s1
	global_load_lds_dwordx4 v[216:217], off
	v_lshl_add_u64 v[216:217], s[40:41], 0, v[134:135]
	s_mov_b32 m0, s42
	s_nop 0
	global_load_lds_dwordx4 v[216:217], off
	v_lshl_add_u64 v[216:217], s[40:41], 0, v[130:131]
	s_add_i32 m0, s42, 0x2000
	s_nop 0
	global_load_lds_dwordx4 v[216:217], off
	v_lshl_add_u64 v[216:217], v[220:221], 0, s[12:13]
	s_mov_b32 m0, s48
	s_nop 0
	global_load_lds_dwordx4 v[216:217], off
	v_lshl_add_u64 v[216:217], v[222:223], 0, s[12:13]
	s_mov_b32 m0, s49
	s_nop 0
	global_load_lds_dwordx4 v[216:217], off
	s_waitcnt vmcnt(8)
	s_waitcnt lgkmcnt(0)
	s_setprio 1
	s_waitcnt lgkmcnt(0)
	s_barrier
	v_mfma_f32_16x16x32_bf16 v[62:65], v[146:149], v[184:187], v[62:65]
	v_mfma_f32_16x16x32_bf16 v[58:61], v[160:163], v[184:187], v[58:61]
	v_mfma_f32_16x16x32_bf16 v[46:49], v[146:149], v[192:195], v[46:49]
	v_mfma_f32_16x16x32_bf16 v[42:45], v[160:163], v[192:195], v[42:45]
	v_mfma_f32_16x16x32_bf16 v[30:33], v[146:149], v[200:203], v[30:33]
	v_mfma_f32_16x16x32_bf16 v[26:29], v[160:163], v[200:203], v[26:29]
	v_mfma_f32_16x16x32_bf16 v[14:17], v[146:149], v[208:211], v[14:17]
	v_mfma_f32_16x16x32_bf16 v[10:13], v[160:163], v[208:211], v[10:13]
	v_mfma_f32_16x16x32_bf16 v[54:57], v[168:171], v[184:187], v[54:57]
	v_mfma_f32_16x16x32_bf16 v[50:53], v[176:179], v[184:187], v[50:53]
	v_mfma_f32_16x16x32_bf16 v[38:41], v[168:171], v[192:195], v[38:41]
	v_mfma_f32_16x16x32_bf16 v[34:37], v[176:179], v[192:195], v[34:37]
	v_mfma_f32_16x16x32_bf16 v[22:25], v[168:171], v[200:203], v[22:25]
	v_mfma_f32_16x16x32_bf16 v[18:21], v[176:179], v[200:203], v[18:21]
	v_mfma_f32_16x16x32_bf16 v[6:9], v[168:171], v[208:211], v[6:9]
	v_mfma_f32_16x16x32_bf16 v[2:5], v[176:179], v[208:211], v[2:5]
	v_mfma_f32_16x16x32_bf16 v[62:65], v[156:159], v[188:191], v[62:65]
	v_mfma_f32_16x16x32_bf16 v[58:61], v[164:167], v[188:191], v[58:61]
	v_mfma_f32_16x16x32_bf16 v[46:49], v[156:159], v[196:199], v[46:49]
	v_mfma_f32_16x16x32_bf16 v[42:45], v[164:167], v[196:199], v[42:45]
	v_mfma_f32_16x16x32_bf16 v[30:33], v[156:159], v[204:207], v[30:33]
	v_mfma_f32_16x16x32_bf16 v[26:29], v[164:167], v[204:207], v[26:29]
	v_mfma_f32_16x16x32_bf16 v[14:17], v[156:159], v[212:215], v[14:17]
	v_mfma_f32_16x16x32_bf16 v[10:13], v[164:167], v[212:215], v[10:13]
	v_mfma_f32_16x16x32_bf16 v[54:57], v[172:175], v[188:191], v[54:57]
	v_mfma_f32_16x16x32_bf16 v[50:53], v[180:183], v[188:191], v[50:53]
	v_mfma_f32_16x16x32_bf16 v[38:41], v[172:175], v[196:199], v[38:41]
	v_mfma_f32_16x16x32_bf16 v[34:37], v[180:183], v[196:199], v[34:37]
	v_mfma_f32_16x16x32_bf16 v[22:25], v[172:175], v[204:207], v[22:25]
	v_mfma_f32_16x16x32_bf16 v[18:21], v[180:183], v[204:207], v[18:21]
	v_mfma_f32_16x16x32_bf16 v[6:9], v[172:175], v[212:215], v[6:9]
	v_mfma_f32_16x16x32_bf16 v[2:5], v[180:183], v[212:215], v[2:5]
	s_setprio 0
	s_barrier
	s_add_i32 s69, s69, 2
	s_add_u32 s38, s38, 0x100
	s_addc_u32 s39, s39, 0
	s_add_u32 s67, s67, 0x100
	s_addc_u32 s68, s68, 0
	s_cmp_gt_u32 s69, 13
	s_cbranch_scc1 .Lpeel_exit_p5
.LBB0_768:
	ds_read_b128 v[146:149], v153
	ds_read_b128 v[156:159], v153 offset:1024
	ds_read_b128 v[160:163], v153 offset:2048
	ds_read_b128 v[164:167], v153 offset:3072
	ds_read_b128 v[168:171], v154
	ds_read_b128 v[172:175], v154 offset:1024
	ds_read_b128 v[176:179], v154 offset:2048
	ds_read_b128 v[180:183], v154 offset:3072
	s_add_u32 s40, s38, 0xfffc0080
	s_addc_u32 s41, s39, -1
	s_cmp_eq_u32 s69, 12
	s_cselect_b32 s43, s0, s41
	s_cselect_b32 s42, s19, s40
	s_cselect_b32 s41, s17, s68
	s_cselect_b32 s40, s66, s67
	v_lshl_add_u64 v[216:217], s[38:39], 0, v[138:139]
	s_add_i32 m0, s29, 0xc000
	ds_read_b128 v[184:187], v155
	ds_read_b128 v[188:191], v155 offset:1024
	ds_read_b128 v[192:195], v155 offset:2048
	ds_read_b128 v[196:199], v155 offset:3072
	ds_read_b128 v[200:203], v155 offset:4096
	ds_read_b128 v[204:207], v155 offset:5120
	ds_read_b128 v[208:211], v155 offset:6144
	ds_read_b128 v[212:215], v155 offset:7168
	global_load_lds_dwordx4 v[216:217], off
	v_lshl_add_u64 v[216:217], s[38:39], 0, v[140:141]
	s_add_i32 m0, s29, 0xe000
	s_nop 0
	global_load_lds_dwordx4 v[216:217], off
	s_waitcnt vmcnt(8)
	s_waitcnt lgkmcnt(0)
	s_setprio 1
	s_waitcnt lgkmcnt(0)
	s_barrier
	v_mfma_f32_16x16x32_bf16 v[126:129], v[146:149], v[184:187], v[126:129]
	v_mfma_f32_16x16x32_bf16 v[122:125], v[160:163], v[184:187], v[122:125]
	v_mfma_f32_16x16x32_bf16 v[110:113], v[146:149], v[192:195], v[110:113]
	v_mfma_f32_16x16x32_bf16 v[106:109], v[160:163], v[192:195], v[106:109]
	v_mfma_f32_16x16x32_bf16 v[94:97], v[146:149], v[200:203], v[94:97]
	v_mfma_f32_16x16x32_bf16 v[90:93], v[160:163], v[200:203], v[90:93]
	v_mfma_f32_16x16x32_bf16 v[78:81], v[146:149], v[208:211], v[78:81]
	v_mfma_f32_16x16x32_bf16 v[74:77], v[160:163], v[208:211], v[74:77]
	v_mfma_f32_16x16x32_bf16 v[118:121], v[168:171], v[184:187], v[118:121]
	v_mfma_f32_16x16x32_bf16 v[114:117], v[176:179], v[184:187], v[114:117]
	v_mfma_f32_16x16x32_bf16 v[102:105], v[168:171], v[192:195], v[102:105]
	v_mfma_f32_16x16x32_bf16 v[98:101], v[176:179], v[192:195], v[98:101]
	v_mfma_f32_16x16x32_bf16 v[86:89], v[168:171], v[200:203], v[86:89]
	v_mfma_f32_16x16x32_bf16 v[82:85], v[176:179], v[200:203], v[82:85]
	v_mfma_f32_16x16x32_bf16 v[70:73], v[168:171], v[208:211], v[70:73]
	v_mfma_f32_16x16x32_bf16 v[66:69], v[176:179], v[208:211], v[66:69]
	v_mfma_f32_16x16x32_bf16 v[126:129], v[156:159], v[188:191], v[126:129]
	v_mfma_f32_16x16x32_bf16 v[122:125], v[164:167], v[188:191], v[122:125]
	v_mfma_f32_16x16x32_bf16 v[110:113], v[156:159], v[196:199], v[110:113]
	v_mfma_f32_16x16x32_bf16 v[106:109], v[164:167], v[196:199], v[106:109]
	v_mfma_f32_16x16x32_bf16 v[94:97], v[156:159], v[204:207], v[94:97]
	v_mfma_f32_16x16x32_bf16 v[90:93], v[164:167], v[204:207], v[90:93]
	v_mfma_f32_16x16x32_bf16 v[78:81], v[156:159], v[212:215], v[78:81]
	v_mfma_f32_16x16x32_bf16 v[74:77], v[164:167], v[212:215], v[74:77]
	v_mfma_f32_16x16x32_bf16 v[118:121], v[172:175], v[188:191], v[118:121]
	v_mfma_f32_16x16x32_bf16 v[114:117], v[180:183], v[188:191], v[114:117]
	v_mfma_f32_16x16x32_bf16 v[102:105], v[172:175], v[196:199], v[102:105]
	v_mfma_f32_16x16x32_bf16 v[98:101], v[180:183], v[196:199], v[98:101]
	v_mfma_f32_16x16x32_bf16 v[86:89], v[172:175], v[204:207], v[86:89]
	v_mfma_f32_16x16x32_bf16 v[82:85], v[180:183], v[204:207], v[82:85]
	v_mfma_f32_16x16x32_bf16 v[70:73], v[172:175], v[212:215], v[70:73]
	v_mfma_f32_16x16x32_bf16 v[66:69], v[180:183], v[212:215], v[66:69]
	s_setprio 0
	s_barrier
	s_add_i32 s70, s51, s1
	v_lshl_add_u64 v[216:217], s[40:41], 0, v[134:135]
	s_mov_b32 m0, s70
	ds_read_b128 v[184:187], v155 offset:16384
	ds_read_b128 v[188:191], v155 offset:17408
	ds_read_b128 v[192:195], v155 offset:18432
	ds_read_b128 v[196:199], v155 offset:19456
	ds_read_b128 v[200:203], v155 offset:20480
	ds_read_b128 v[204:207], v155 offset:21504
	ds_read_b128 v[208:211], v155 offset:22528
	ds_read_b128 v[212:215], v155 offset:23552
	global_load_lds_dwordx4 v[216:217], off
	s_add_i32 m0, s70, 0x2000
	s_add_u32 s70, s40, 0x40000
	v_lshl_add_u64 v[218:219], s[40:41], 0, v[130:131]
	s_addc_u32 s71, s41, 0
	s_add_i32 s72, s60, s1
	global_load_lds_dwordx4 v[218:219], off
	v_lshl_add_u64 v[220:221], s[70:71], 0, v[134:135]
	s_mov_b32 m0, s72
	v_lshl_add_u64 v[222:223], s[42:43], 0, v[132:133]
	global_load_lds_dwordx4 v[220:221], off
	v_lshl_add_u64 v[220:221], s[70:71], 0, v[130:131]
	s_add_i32 m0, s72, 0x2000
	s_nop 0
	global_load_lds_dwordx4 v[220:221], off
	v_lshl_add_u64 v[220:221], s[42:43], 0, v[136:137]
	s_mov_b32 m0, s29
	s_nop 0
	global_load_lds_dwordx4 v[220:221], off
	s_mov_b32 m0, s37
	s_nop 0
	global_load_lds_dwordx4 v[222:223], off
	s_waitcnt vmcnt(8)
	s_waitcnt lgkmcnt(0)
	s_setprio 1
	s_waitcnt lgkmcnt(0)
	s_barrier
	v_mfma_f32_16x16x32_bf16 v[62:65], v[146:149], v[184:187], v[62:65]
	v_mfma_f32_16x16x32_bf16 v[58:61], v[160:163], v[184:187], v[58:61]
	v_mfma_f32_16x16x32_bf16 v[46:49], v[146:149], v[192:195], v[46:49]
	v_mfma_f32_16x16x32_bf16 v[42:45], v[160:163], v[192:195], v[42:45]
	v_mfma_f32_16x16x32_bf16 v[30:33], v[146:149], v[200:203], v[30:33]
	v_mfma_f32_16x16x32_bf16 v[26:29], v[160:163], v[200:203], v[26:29]
	v_mfma_f32_16x16x32_bf16 v[14:17], v[146:149], v[208:211], v[14:17]
	v_mfma_f32_16x16x32_bf16 v[10:13], v[160:163], v[208:211], v[10:13]
	v_mfma_f32_16x16x32_bf16 v[54:57], v[168:171], v[184:187], v[54:57]
	v_mfma_f32_16x16x32_bf16 v[50:53], v[176:179], v[184:187], v[50:53]
	v_mfma_f32_16x16x32_bf16 v[38:41], v[168:171], v[192:195], v[38:41]
	v_mfma_f32_16x16x32_bf16 v[34:37], v[176:179], v[192:195], v[34:37]
	v_mfma_f32_16x16x32_bf16 v[22:25], v[168:171], v[200:203], v[22:25]
	v_mfma_f32_16x16x32_bf16 v[18:21], v[176:179], v[200:203], v[18:21]
	v_mfma_f32_16x16x32_bf16 v[6:9], v[168:171], v[208:211], v[6:9]
	v_mfma_f32_16x16x32_bf16 v[2:5], v[176:179], v[208:211], v[2:5]
	v_mfma_f32_16x16x32_bf16 v[62:65], v[156:159], v[188:191], v[62:65]
	v_mfma_f32_16x16x32_bf16 v[58:61], v[164:167], v[188:191], v[58:61]
	v_mfma_f32_16x16x32_bf16 v[46:49], v[156:159], v[196:199], v[46:49]
	v_mfma_f32_16x16x32_bf16 v[42:45], v[164:167], v[196:199], v[42:45]
	v_mfma_f32_16x16x32_bf16 v[30:33], v[156:159], v[204:207], v[30:33]
	v_mfma_f32_16x16x32_bf16 v[26:29], v[164:167], v[204:207], v[26:29]
	v_mfma_f32_16x16x32_bf16 v[14:17], v[156:159], v[212:215], v[14:17]
	v_mfma_f32_16x16x32_bf16 v[10:13], v[164:167], v[212:215], v[10:13]
	v_mfma_f32_16x16x32_bf16 v[54:57], v[172:175], v[188:191], v[54:57]
	v_mfma_f32_16x16x32_bf16 v[50:53], v[180:183], v[188:191], v[50:53]
	v_mfma_f32_16x16x32_bf16 v[38:41], v[172:175], v[196:199], v[38:41]
	v_mfma_f32_16x16x32_bf16 v[34:37], v[180:183], v[196:199], v[34:37]
	v_mfma_f32_16x16x32_bf16 v[22:25], v[172:175], v[204:207], v[22:25]
	v_mfma_f32_16x16x32_bf16 v[18:21], v[180:183], v[204:207], v[18:21]
	v_mfma_f32_16x16x32_bf16 v[6:9], v[172:175], v[212:215], v[6:9]
	v_mfma_f32_16x16x32_bf16 v[2:5], v[180:183], v[212:215], v[2:5]
	s_setprio 0
	s_barrier
	s_add_i32 s70, 0, 0x18000
	s_add_i32 s71, 0, 0x1c000
	v_add_u32_e32 v164, s70, v151
	v_add_u32_e32 v180, s71, v151
	ds_read_b128 v[146:149], v164
	ds_read_b128 v[156:159], v164 offset:1024
	ds_read_b128 v[160:163], v164 offset:2048
	ds_read_b128 v[164:167], v164 offset:3072
	ds_read_b128 v[168:171], v180
	ds_read_b128 v[172:175], v180 offset:1024
	ds_read_b128 v[176:179], v180 offset:2048
	ds_read_b128 v[180:183], v180 offset:3072
	s_add_u32 s42, s42, 0x40000
	s_addc_u32 s43, s43, 0
	s_mov_b32 m0, s45
	v_lshl_add_u64 v[224:225], s[42:43], 0, v[136:137]
	ds_read_b128 v[184:187], v155 offset:32768
	ds_read_b128 v[188:191], v155 offset:33792
	ds_read_b128 v[192:195], v155 offset:34816
	ds_read_b128 v[196:199], v155 offset:35840
	ds_read_b128 v[200:203], v155 offset:36864
	ds_read_b128 v[204:207], v155 offset:37888
	ds_read_b128 v[208:211], v155 offset:38912
	ds_read_b128 v[212:215], v155 offset:39936
	global_load_lds_dwordx4 v[224:225], off
	v_lshl_add_u64 v[224:225], s[42:43], 0, v[132:133]
	s_mov_b32 m0, s46
	s_nop 0
	global_load_lds_dwordx4 v[224:225], off
	s_waitcnt vmcnt(8)
	s_waitcnt lgkmcnt(0)
	s_setprio 1
	s_waitcnt lgkmcnt(0)
	s_barrier
	v_mfma_f32_16x16x32_bf16 v[126:129], v[146:149], v[184:187], v[126:129]
	v_mfma_f32_16x16x32_bf16 v[122:125], v[160:163], v[184:187], v[122:125]
	v_mfma_f32_16x16x32_bf16 v[110:113], v[146:149], v[192:195], v[110:113]
	v_mfma_f32_16x16x32_bf16 v[106:109], v[160:163], v[192:195], v[106:109]
	v_mfma_f32_16x16x32_bf16 v[94:97], v[146:149], v[200:203], v[94:97]
	v_mfma_f32_16x16x32_bf16 v[90:93], v[160:163], v[200:203], v[90:93]
	v_mfma_f32_16x16x32_bf16 v[78:81], v[146:149], v[208:211], v[78:81]
	v_mfma_f32_16x16x32_bf16 v[74:77], v[160:163], v[208:211], v[74:77]
	v_mfma_f32_16x16x32_bf16 v[118:121], v[168:171], v[184:187], v[118:121]
	v_mfma_f32_16x16x32_bf16 v[114:117], v[176:179], v[184:187], v[114:117]
	v_mfma_f32_16x16x32_bf16 v[102:105], v[168:171], v[192:195], v[102:105]
	v_mfma_f32_16x16x32_bf16 v[98:101], v[176:179], v[192:195], v[98:101]
	v_mfma_f32_16x16x32_bf16 v[86:89], v[168:171], v[200:203], v[86:89]
	v_mfma_f32_16x16x32_bf16 v[82:85], v[176:179], v[200:203], v[82:85]
	v_mfma_f32_16x16x32_bf16 v[70:73], v[168:171], v[208:211], v[70:73]
	v_mfma_f32_16x16x32_bf16 v[66:69], v[176:179], v[208:211], v[66:69]
	v_mfma_f32_16x16x32_bf16 v[126:129], v[156:159], v[188:191], v[126:129]
	v_mfma_f32_16x16x32_bf16 v[122:125], v[164:167], v[188:191], v[122:125]
	v_mfma_f32_16x16x32_bf16 v[110:113], v[156:159], v[196:199], v[110:113]
	v_mfma_f32_16x16x32_bf16 v[106:109], v[164:167], v[196:199], v[106:109]
	v_mfma_f32_16x16x32_bf16 v[94:97], v[156:159], v[204:207], v[94:97]
	v_mfma_f32_16x16x32_bf16 v[90:93], v[164:167], v[204:207], v[90:93]
	v_mfma_f32_16x16x32_bf16 v[78:81], v[156:159], v[212:215], v[78:81]
	v_mfma_f32_16x16x32_bf16 v[74:77], v[164:167], v[212:215], v[74:77]
	v_mfma_f32_16x16x32_bf16 v[118:121], v[172:175], v[188:191], v[118:121]
	v_mfma_f32_16x16x32_bf16 v[114:117], v[180:183], v[188:191], v[114:117]
	v_mfma_f32_16x16x32_bf16 v[102:105], v[172:175], v[196:199], v[102:105]
	v_mfma_f32_16x16x32_bf16 v[98:101], v[180:183], v[196:199], v[98:101]
	v_mfma_f32_16x16x32_bf16 v[86:89], v[172:175], v[204:207], v[86:89]
	v_mfma_f32_16x16x32_bf16 v[82:85], v[180:183], v[204:207], v[82:85]
	v_mfma_f32_16x16x32_bf16 v[70:73], v[172:175], v[212:215], v[70:73]
	v_mfma_f32_16x16x32_bf16 v[66:69], v[180:183], v[212:215], v[66:69]
	s_setprio 0
	s_barrier
	s_add_i32 s42, s70, s1
	v_lshl_add_u64 v[216:217], v[216:217], 0, s[12:13]
	s_mov_b32 m0, s42
	ds_read_b128 v[184:187], v155 offset:49152
	ds_read_b128 v[188:191], v155 offset:50176
	ds_read_b128 v[192:195], v155 offset:51200
	ds_read_b128 v[196:199], v155 offset:52224
	ds_read_b128 v[200:203], v155 offset:53248
	ds_read_b128 v[204:207], v155 offset:54272
	ds_read_b128 v[208:211], v155 offset:55296
	ds_read_b128 v[212:215], v155 offset:56320
	global_load_lds_dwordx4 v[216:217], off
	s_add_i32 m0, s42, 0x2000
	s_add_u32 s40, s40, 0x40080
	v_lshl_add_u64 v[216:217], v[218:219], 0, s[12:13]
	s_addc_u32 s41, s41, 0
	s_add_i32 s42, s71, s1
	global_load_lds_dwordx4 v[216:217], off
	v_lshl_add_u64 v[216:217], s[40:41], 0, v[134:135]
	s_mov_b32 m0, s42
	s_nop 0
	global_load_lds_dwordx4 v[216:217], off
	v_lshl_add_u64 v[216:217], s[40:41], 0, v[130:131]
	s_add_i32 m0, s42, 0x2000
	s_nop 0
	global_load_lds_dwordx4 v[216:217], off
	v_lshl_add_u64 v[216:217], v[220:221], 0, s[12:13]
	s_mov_b32 m0, s48
	s_nop 0
	global_load_lds_dwordx4 v[216:217], off
	v_lshl_add_u64 v[216:217], v[222:223], 0, s[12:13]
	s_mov_b32 m0, s49
	s_nop 0
	global_load_lds_dwordx4 v[216:217], off
	s_waitcnt vmcnt(8)
	s_waitcnt lgkmcnt(0)
	s_setprio 1
	s_waitcnt lgkmcnt(0)
	s_barrier
	v_mfma_f32_16x16x32_bf16 v[62:65], v[146:149], v[184:187], v[62:65]
	v_mfma_f32_16x16x32_bf16 v[58:61], v[160:163], v[184:187], v[58:61]
	v_mfma_f32_16x16x32_bf16 v[46:49], v[146:149], v[192:195], v[46:49]
	v_mfma_f32_16x16x32_bf16 v[42:45], v[160:163], v[192:195], v[42:45]
	v_mfma_f32_16x16x32_bf16 v[30:33], v[146:149], v[200:203], v[30:33]
	v_mfma_f32_16x16x32_bf16 v[26:29], v[160:163], v[200:203], v[26:29]
	v_mfma_f32_16x16x32_bf16 v[14:17], v[146:149], v[208:211], v[14:17]
	v_mfma_f32_16x16x32_bf16 v[10:13], v[160:163], v[208:211], v[10:13]
	v_mfma_f32_16x16x32_bf16 v[54:57], v[168:171], v[184:187], v[54:57]
	v_mfma_f32_16x16x32_bf16 v[50:53], v[176:179], v[184:187], v[50:53]
	v_mfma_f32_16x16x32_bf16 v[38:41], v[168:171], v[192:195], v[38:41]
	v_mfma_f32_16x16x32_bf16 v[34:37], v[176:179], v[192:195], v[34:37]
	v_mfma_f32_16x16x32_bf16 v[22:25], v[168:171], v[200:203], v[22:25]
	v_mfma_f32_16x16x32_bf16 v[18:21], v[176:179], v[200:203], v[18:21]
	v_mfma_f32_16x16x32_bf16 v[6:9], v[168:171], v[208:211], v[6:9]
	v_mfma_f32_16x16x32_bf16 v[2:5], v[176:179], v[208:211], v[2:5]
	v_mfma_f32_16x16x32_bf16 v[62:65], v[156:159], v[188:191], v[62:65]
	v_mfma_f32_16x16x32_bf16 v[58:61], v[164:167], v[188:191], v[58:61]
	v_mfma_f32_16x16x32_bf16 v[46:49], v[156:159], v[196:199], v[46:49]
	v_mfma_f32_16x16x32_bf16 v[42:45], v[164:167], v[196:199], v[42:45]
	v_mfma_f32_16x16x32_bf16 v[30:33], v[156:159], v[204:207], v[30:33]
	v_mfma_f32_16x16x32_bf16 v[26:29], v[164:167], v[204:207], v[26:29]
	v_mfma_f32_16x16x32_bf16 v[14:17], v[156:159], v[212:215], v[14:17]
	v_mfma_f32_16x16x32_bf16 v[10:13], v[164:167], v[212:215], v[10:13]
	v_mfma_f32_16x16x32_bf16 v[54:57], v[172:175], v[188:191], v[54:57]
	v_mfma_f32_16x16x32_bf16 v[50:53], v[180:183], v[188:191], v[50:53]
	v_mfma_f32_16x16x32_bf16 v[38:41], v[172:175], v[196:199], v[38:41]
	v_mfma_f32_16x16x32_bf16 v[34:37], v[180:183], v[196:199], v[34:37]
	v_mfma_f32_16x16x32_bf16 v[22:25], v[172:175], v[204:207], v[22:25]
	v_mfma_f32_16x16x32_bf16 v[18:21], v[180:183], v[204:207], v[18:21]
	v_mfma_f32_16x16x32_bf16 v[6:9], v[172:175], v[212:215], v[6:9]
	v_mfma_f32_16x16x32_bf16 v[2:5], v[180:183], v[212:215], v[2:5]
	s_setprio 0
	s_barrier
	s_add_i32 s69, s69, 2
	s_add_u32 s38, s38, 0x100
	s_addc_u32 s39, s39, 0
	s_add_u32 s67, s67, 0x100
	s_addc_u32 s68, s68, 0
	s_cmp_gt_u32 s69, 13
	s_cbranch_scc0 .LBB0_768

.LBB0_874:
	v_add_u32_e32 v164, s44, v150
	v_add_u32_e32 v180, s45, v150
	s_add_u32 s24, s12, s20
	ds_read_b128 v[152:155], v164
	ds_read_b128 v[156:159], v164 offset:1024
	ds_read_b128 v[160:163], v164 offset:2048
	ds_read_b128 v[164:167], v164 offset:3072
	ds_read_b128 v[168:171], v180
	ds_read_b128 v[172:175], v180 offset:1024
	ds_read_b128 v[176:179], v180 offset:2048
	ds_read_b128 v[180:183], v180 offset:3072
	s_addc_u32 s25, s13, s21
	s_add_u32 s24, s24, 0x100
	s_addc_u32 s25, s25, 0
	s_add_u32 s50, s17, s20
	s_addc_u32 s51, s48, s21
	s_cmpk_eq_i32 s20, 0x1500
	s_cselect_b32 s27, s19, s25
	s_cselect_b32 s26, s18, s24
	s_cselect_b32 s25, s7, s51
	s_cselect_b32 s24, s6, s50
	v_lshl_add_u64 v[208:209], v[146:147], 0, s[20:21]
	s_add_i32 m0, s37, 0xc000
	ds_read_b128 v[184:187], v151
	ds_read_b128 v[188:191], v151 offset:1024
	ds_read_b128 v[192:195], v151 offset:2048
	ds_read_b128 v[196:199], v151 offset:3072
	ds_read_b128 v[200:203], v151 offset:4096
	ds_read_b128 v[204:207], v151 offset:5120
	ds_read_b128 v[214:217], v151 offset:6144
	ds_read_b128 v[218:221], v151 offset:7168
	global_load_lds_dwordx4 v[208:209], off
	v_lshl_add_u64 v[208:209], v[148:149], 0, s[20:21]
	s_add_i32 m0, s37, 0xe000
	s_nop 0
	global_load_lds_dwordx4 v[208:209], off
	s_waitcnt vmcnt(8)
	s_waitcnt lgkmcnt(0)
	s_setprio 1
	s_waitcnt lgkmcnt(0)
	s_barrier
	v_mfma_f32_16x16x32_bf16 v[126:129], v[152:155], v[184:187], v[126:129]
	v_mfma_f32_16x16x32_bf16 v[122:125], v[160:163], v[184:187], v[122:125]
	v_mfma_f32_16x16x32_bf16 v[110:113], v[152:155], v[192:195], v[110:113]
	v_mfma_f32_16x16x32_bf16 v[106:109], v[160:163], v[192:195], v[106:109]
	v_mfma_f32_16x16x32_bf16 v[94:97], v[152:155], v[200:203], v[94:97]
	v_mfma_f32_16x16x32_bf16 v[90:93], v[160:163], v[200:203], v[90:93]
	v_mfma_f32_16x16x32_bf16 v[78:81], v[152:155], v[214:217], v[78:81]
	v_mfma_f32_16x16x32_bf16 v[74:77], v[160:163], v[214:217], v[74:77]
	v_mfma_f32_16x16x32_bf16 v[118:121], v[168:171], v[184:187], v[118:121]
	v_mfma_f32_16x16x32_bf16 v[114:117], v[176:179], v[184:187], v[114:117]
	v_mfma_f32_16x16x32_bf16 v[102:105], v[168:171], v[192:195], v[102:105]
	v_mfma_f32_16x16x32_bf16 v[98:101], v[176:179], v[192:195], v[98:101]
	v_mfma_f32_16x16x32_bf16 v[86:89], v[168:171], v[200:203], v[86:89]
	v_mfma_f32_16x16x32_bf16 v[82:85], v[176:179], v[200:203], v[82:85]
	v_mfma_f32_16x16x32_bf16 v[70:73], v[168:171], v[214:217], v[70:73]
	v_mfma_f32_16x16x32_bf16 v[66:69], v[176:179], v[214:217], v[66:69]
	v_mfma_f32_16x16x32_bf16 v[126:129], v[156:159], v[188:191], v[126:129]
	v_mfma_f32_16x16x32_bf16 v[122:125], v[164:167], v[188:191], v[122:125]
	v_mfma_f32_16x16x32_bf16 v[110:113], v[156:159], v[196:199], v[110:113]
	v_mfma_f32_16x16x32_bf16 v[106:109], v[164:167], v[196:199], v[106:109]
	v_mfma_f32_16x16x32_bf16 v[94:97], v[156:159], v[204:207], v[94:97]
	v_mfma_f32_16x16x32_bf16 v[90:93], v[164:167], v[204:207], v[90:93]
	v_mfma_f32_16x16x32_bf16 v[78:81], v[156:159], v[218:221], v[78:81]
	v_mfma_f32_16x16x32_bf16 v[74:77], v[164:167], v[218:221], v[74:77]
	v_mfma_f32_16x16x32_bf16 v[118:121], v[172:175], v[188:191], v[118:121]
	v_mfma_f32_16x16x32_bf16 v[114:117], v[180:183], v[188:191], v[114:117]
	v_mfma_f32_16x16x32_bf16 v[102:105], v[172:175], v[196:199], v[102:105]
	v_mfma_f32_16x16x32_bf16 v[98:101], v[180:183], v[196:199], v[98:101]
	v_mfma_f32_16x16x32_bf16 v[86:89], v[172:175], v[204:207], v[86:89]
	v_mfma_f32_16x16x32_bf16 v[82:85], v[180:183], v[204:207], v[82:85]
	v_mfma_f32_16x16x32_bf16 v[70:73], v[172:175], v[218:221], v[70:73]
	v_mfma_f32_16x16x32_bf16 v[66:69], v[180:183], v[218:221], v[66:69]
	s_setprio 0
	s_barrier
	s_add_i32 s50, s44, s36
	v_lshl_add_u64 v[208:209], s[24:25], 0, v[132:133]
	s_mov_b32 m0, s50
	ds_read_b128 v[184:187], v151 offset:16384
	ds_read_b128 v[188:191], v151 offset:17408
	ds_read_b128 v[192:195], v151 offset:18432
	ds_read_b128 v[196:199], v151 offset:19456
	ds_read_b128 v[200:203], v151 offset:20480
	ds_read_b128 v[204:207], v151 offset:21504
	ds_read_b128 v[214:217], v151 offset:22528
	ds_read_b128 v[218:221], v151 offset:23552
	global_load_lds_dwordx4 v[208:209], off
	s_add_i32 m0, s50, 0x2000
	s_add_u32 s50, s24, 0xb0000
	v_lshl_add_u64 v[222:223], s[24:25], 0, v[136:137]
	s_addc_u32 s51, s25, 0
	s_add_i32 s56, s45, s36
	global_load_lds_dwordx4 v[222:223], off
	v_lshl_add_u64 v[224:225], s[50:51], 0, v[132:133]
	s_mov_b32 m0, s56
	v_lshl_add_u64 v[226:227], s[26:27], 0, v[134:135]
	global_load_lds_dwordx4 v[224:225], off
	v_lshl_add_u64 v[224:225], s[50:51], 0, v[136:137]
	s_add_i32 m0, s56, 0x2000
	s_nop 0
	global_load_lds_dwordx4 v[224:225], off
	v_lshl_add_u64 v[224:225], s[26:27], 0, v[130:131]
	s_mov_b32 m0, s37
	s_nop 0
	global_load_lds_dwordx4 v[224:225], off
	s_mov_b32 m0, s38
	s_nop 0
	global_load_lds_dwordx4 v[226:227], off
	s_waitcnt vmcnt(8)
	s_waitcnt lgkmcnt(0)
	s_setprio 1
	s_waitcnt lgkmcnt(0)
	s_barrier
	v_mfma_f32_16x16x32_bf16 v[62:65], v[152:155], v[184:187], v[62:65]
	v_mfma_f32_16x16x32_bf16 v[58:61], v[160:163], v[184:187], v[58:61]
	v_mfma_f32_16x16x32_bf16 v[46:49], v[152:155], v[192:195], v[46:49]
	v_mfma_f32_16x16x32_bf16 v[42:45], v[160:163], v[192:195], v[42:45]
	v_mfma_f32_16x16x32_bf16 v[30:33], v[152:155], v[200:203], v[30:33]
	v_mfma_f32_16x16x32_bf16 v[26:29], v[160:163], v[200:203], v[26:29]
	v_mfma_f32_16x16x32_bf16 v[14:17], v[152:155], v[214:217], v[14:17]
	v_mfma_f32_16x16x32_bf16 v[10:13], v[160:163], v[214:217], v[10:13]
	v_mfma_f32_16x16x32_bf16 v[54:57], v[168:171], v[184:187], v[54:57]
	v_mfma_f32_16x16x32_bf16 v[50:53], v[176:179], v[184:187], v[50:53]
	v_mfma_f32_16x16x32_bf16 v[38:41], v[168:171], v[192:195], v[38:41]
	v_mfma_f32_16x16x32_bf16 v[34:37], v[176:179], v[192:195], v[34:37]
	v_mfma_f32_16x16x32_bf16 v[22:25], v[168:171], v[200:203], v[22:25]
	v_mfma_f32_16x16x32_bf16 v[18:21], v[176:179], v[200:203], v[18:21]
	v_mfma_f32_16x16x32_bf16 v[6:9], v[168:171], v[214:217], v[6:9]
	v_mfma_f32_16x16x32_bf16 v[2:5], v[176:179], v[214:217], v[2:5]
	v_mfma_f32_16x16x32_bf16 v[62:65], v[156:159], v[188:191], v[62:65]
	v_mfma_f32_16x16x32_bf16 v[58:61], v[164:167], v[188:191], v[58:61]
	v_mfma_f32_16x16x32_bf16 v[46:49], v[156:159], v[196:199], v[46:49]
	v_mfma_f32_16x16x32_bf16 v[42:45], v[164:167], v[196:199], v[42:45]
	v_mfma_f32_16x16x32_bf16 v[30:33], v[156:159], v[204:207], v[30:33]
	v_mfma_f32_16x16x32_bf16 v[26:29], v[164:167], v[204:207], v[26:29]
	v_mfma_f32_16x16x32_bf16 v[14:17], v[156:159], v[218:221], v[14:17]
	v_mfma_f32_16x16x32_bf16 v[10:13], v[164:167], v[218:221], v[10:13]
	v_mfma_f32_16x16x32_bf16 v[54:57], v[172:175], v[188:191], v[54:57]
	v_mfma_f32_16x16x32_bf16 v[50:53], v[180:183], v[188:191], v[50:53]
	v_mfma_f32_16x16x32_bf16 v[38:41], v[172:175], v[196:199], v[38:41]
	v_mfma_f32_16x16x32_bf16 v[34:37], v[180:183], v[196:199], v[34:37]
	v_mfma_f32_16x16x32_bf16 v[22:25], v[172:175], v[204:207], v[22:25]
	v_mfma_f32_16x16x32_bf16 v[18:21], v[180:183], v[204:207], v[18:21]
	v_mfma_f32_16x16x32_bf16 v[6:9], v[172:175], v[218:221], v[6:9]
	v_mfma_f32_16x16x32_bf16 v[2:5], v[180:183], v[218:221], v[2:5]
	s_setprio 0
	s_barrier
	s_add_i32 s50, 0, 0x18000
	s_add_i32 s51, 0, 0x1c000
	v_add_u32_e32 v164, s50, v150
	v_add_u32_e32 v180, s51, v150
	ds_read_b128 v[152:155], v164
	ds_read_b128 v[156:159], v164 offset:1024
	ds_read_b128 v[160:163], v164 offset:2048
	ds_read_b128 v[164:167], v164 offset:3072
	ds_read_b128 v[168:171], v180
	ds_read_b128 v[172:175], v180 offset:1024
	ds_read_b128 v[176:179], v180 offset:2048
	ds_read_b128 v[180:183], v180 offset:3072
	s_add_u32 s26, s26, 0xb0000
	s_addc_u32 s27, s27, 0
	s_mov_b32 m0, s39
	v_lshl_add_u64 v[228:229], s[26:27], 0, v[130:131]
	ds_read_b128 v[184:187], v151 offset:32768
	ds_read_b128 v[188:191], v151 offset:33792
	ds_read_b128 v[192:195], v151 offset:34816
	ds_read_b128 v[196:199], v151 offset:35840
	ds_read_b128 v[200:203], v151 offset:36864
	ds_read_b128 v[204:207], v151 offset:37888
	ds_read_b128 v[214:217], v151 offset:38912
	ds_read_b128 v[218:221], v151 offset:39936
	global_load_lds_dwordx4 v[228:229], off
	v_lshl_add_u64 v[228:229], s[26:27], 0, v[134:135]
	s_mov_b32 m0, s40
	s_nop 0
	global_load_lds_dwordx4 v[228:229], off
	s_waitcnt vmcnt(8)
	s_waitcnt lgkmcnt(0)
	s_setprio 1
	s_waitcnt lgkmcnt(0)
	s_barrier
	v_mfma_f32_16x16x32_bf16 v[126:129], v[152:155], v[184:187], v[126:129]
	v_mfma_f32_16x16x32_bf16 v[122:125], v[160:163], v[184:187], v[122:125]
	v_mfma_f32_16x16x32_bf16 v[110:113], v[152:155], v[192:195], v[110:113]
	v_mfma_f32_16x16x32_bf16 v[106:109], v[160:163], v[192:195], v[106:109]
	v_mfma_f32_16x16x32_bf16 v[94:97], v[152:155], v[200:203], v[94:97]
	v_mfma_f32_16x16x32_bf16 v[90:93], v[160:163], v[200:203], v[90:93]
	v_mfma_f32_16x16x32_bf16 v[78:81], v[152:155], v[214:217], v[78:81]
	v_mfma_f32_16x16x32_bf16 v[74:77], v[160:163], v[214:217], v[74:77]
	v_mfma_f32_16x16x32_bf16 v[118:121], v[168:171], v[184:187], v[118:121]
	v_mfma_f32_16x16x32_bf16 v[114:117], v[176:179], v[184:187], v[114:117]
	v_mfma_f32_16x16x32_bf16 v[102:105], v[168:171], v[192:195], v[102:105]
	v_mfma_f32_16x16x32_bf16 v[98:101], v[176:179], v[192:195], v[98:101]
	v_mfma_f32_16x16x32_bf16 v[86:89], v[168:171], v[200:203], v[86:89]
	v_mfma_f32_16x16x32_bf16 v[82:85], v[176:179], v[200:203], v[82:85]
	v_mfma_f32_16x16x32_bf16 v[70:73], v[168:171], v[214:217], v[70:73]
	v_mfma_f32_16x16x32_bf16 v[66:69], v[176:179], v[214:217], v[66:69]
	v_mfma_f32_16x16x32_bf16 v[126:129], v[156:159], v[188:191], v[126:129]
	v_mfma_f32_16x16x32_bf16 v[122:125], v[164:167], v[188:191], v[122:125]
	v_mfma_f32_16x16x32_bf16 v[110:113], v[156:159], v[196:199], v[110:113]
	v_mfma_f32_16x16x32_bf16 v[106:109], v[164:167], v[196:199], v[106:109]
	v_mfma_f32_16x16x32_bf16 v[94:97], v[156:159], v[204:207], v[94:97]
	v_mfma_f32_16x16x32_bf16 v[90:93], v[164:167], v[204:207], v[90:93]
	v_mfma_f32_16x16x32_bf16 v[78:81], v[156:159], v[218:221], v[78:81]
	v_mfma_f32_16x16x32_bf16 v[74:77], v[164:167], v[218:221], v[74:77]
	v_mfma_f32_16x16x32_bf16 v[118:121], v[172:175], v[188:191], v[118:121]
	v_mfma_f32_16x16x32_bf16 v[114:117], v[180:183], v[188:191], v[114:117]
	v_mfma_f32_16x16x32_bf16 v[102:105], v[172:175], v[196:199], v[102:105]
	v_mfma_f32_16x16x32_bf16 v[98:101], v[180:183], v[196:199], v[98:101]
	v_mfma_f32_16x16x32_bf16 v[86:89], v[172:175], v[204:207], v[86:89]
	v_mfma_f32_16x16x32_bf16 v[82:85], v[180:183], v[204:207], v[82:85]
	v_mfma_f32_16x16x32_bf16 v[70:73], v[172:175], v[218:221], v[70:73]
	v_mfma_f32_16x16x32_bf16 v[66:69], v[180:183], v[218:221], v[66:69]
	s_setprio 0
	s_barrier
	s_add_i32 s26, s50, s36
	v_lshl_add_u64 v[208:209], v[208:209], 0, s[14:15]
	s_mov_b32 m0, s26
	ds_read_b128 v[184:187], v151 offset:49152
	ds_read_b128 v[188:191], v151 offset:50176
	ds_read_b128 v[192:195], v151 offset:51200
	ds_read_b128 v[196:199], v151 offset:52224
	ds_read_b128 v[200:203], v151 offset:53248
	ds_read_b128 v[204:207], v151 offset:54272
	ds_read_b128 v[214:217], v151 offset:55296
	ds_read_b128 v[218:221], v151 offset:56320
	global_load_lds_dwordx4 v[208:209], off
	s_add_i32 m0, s26, 0x2000
	s_add_u32 s24, s24, 0xb0080
	v_lshl_add_u64 v[208:209], v[222:223], 0, s[14:15]
	s_addc_u32 s25, s25, 0
	s_add_i32 s26, s51, s36
	global_load_lds_dwordx4 v[208:209], off
	v_lshl_add_u64 v[208:209], s[24:25], 0, v[132:133]
	s_mov_b32 m0, s26
	s_nop 0
	global_load_lds_dwordx4 v[208:209], off
	v_lshl_add_u64 v[208:209], s[24:25], 0, v[136:137]
	s_add_i32 m0, s26, 0x2000
	s_nop 0
	global_load_lds_dwordx4 v[208:209], off
	v_lshl_add_u64 v[208:209], v[224:225], 0, s[14:15]
	s_mov_b32 m0, s41
	s_nop 0
	global_load_lds_dwordx4 v[208:209], off
	v_lshl_add_u64 v[208:209], v[226:227], 0, s[14:15]
	s_mov_b32 m0, s42
	s_nop 0
	global_load_lds_dwordx4 v[208:209], off
	s_waitcnt vmcnt(8)
	s_waitcnt lgkmcnt(0)
	s_setprio 1
	s_waitcnt lgkmcnt(0)
	s_barrier
	v_mfma_f32_16x16x32_bf16 v[62:65], v[152:155], v[184:187], v[62:65]
	v_mfma_f32_16x16x32_bf16 v[58:61], v[160:163], v[184:187], v[58:61]
	v_mfma_f32_16x16x32_bf16 v[46:49], v[152:155], v[192:195], v[46:49]
	v_mfma_f32_16x16x32_bf16 v[42:45], v[160:163], v[192:195], v[42:45]
	v_mfma_f32_16x16x32_bf16 v[30:33], v[152:155], v[200:203], v[30:33]
	v_mfma_f32_16x16x32_bf16 v[26:29], v[160:163], v[200:203], v[26:29]
	v_mfma_f32_16x16x32_bf16 v[14:17], v[152:155], v[214:217], v[14:17]
	v_mfma_f32_16x16x32_bf16 v[10:13], v[160:163], v[214:217], v[10:13]
	v_mfma_f32_16x16x32_bf16 v[54:57], v[168:171], v[184:187], v[54:57]
	v_mfma_f32_16x16x32_bf16 v[50:53], v[176:179], v[184:187], v[50:53]
	v_mfma_f32_16x16x32_bf16 v[38:41], v[168:171], v[192:195], v[38:41]
	v_mfma_f32_16x16x32_bf16 v[34:37], v[176:179], v[192:195], v[34:37]
	v_mfma_f32_16x16x32_bf16 v[22:25], v[168:171], v[200:203], v[22:25]
	v_mfma_f32_16x16x32_bf16 v[18:21], v[176:179], v[200:203], v[18:21]
	v_mfma_f32_16x16x32_bf16 v[6:9], v[168:171], v[214:217], v[6:9]
	v_mfma_f32_16x16x32_bf16 v[2:5], v[176:179], v[214:217], v[2:5]
	v_mfma_f32_16x16x32_bf16 v[62:65], v[156:159], v[188:191], v[62:65]
	v_mfma_f32_16x16x32_bf16 v[58:61], v[164:167], v[188:191], v[58:61]
	v_mfma_f32_16x16x32_bf16 v[46:49], v[156:159], v[196:199], v[46:49]
	v_mfma_f32_16x16x32_bf16 v[42:45], v[164:167], v[196:199], v[42:45]
	v_mfma_f32_16x16x32_bf16 v[30:33], v[156:159], v[204:207], v[30:33]
	v_mfma_f32_16x16x32_bf16 v[26:29], v[164:167], v[204:207], v[26:29]
	v_mfma_f32_16x16x32_bf16 v[14:17], v[156:159], v[218:221], v[14:17]
	v_mfma_f32_16x16x32_bf16 v[10:13], v[164:167], v[218:221], v[10:13]
	v_mfma_f32_16x16x32_bf16 v[54:57], v[172:175], v[188:191], v[54:57]
	v_mfma_f32_16x16x32_bf16 v[50:53], v[180:183], v[188:191], v[50:53]
	v_mfma_f32_16x16x32_bf16 v[38:41], v[172:175], v[196:199], v[38:41]
	v_mfma_f32_16x16x32_bf16 v[34:37], v[180:183], v[196:199], v[34:37]
	v_mfma_f32_16x16x32_bf16 v[22:25], v[172:175], v[204:207], v[22:25]
	v_mfma_f32_16x16x32_bf16 v[18:21], v[180:183], v[204:207], v[18:21]
	v_mfma_f32_16x16x32_bf16 v[6:9], v[172:175], v[218:221], v[6:9]
	v_mfma_f32_16x16x32_bf16 v[2:5], v[180:183], v[218:221], v[2:5]
	s_setprio 0
	s_barrier
	s_add_i32 s49, s49, 2
	s_add_u32 s20, s20, 0x100
	s_addc_u32 s21, s21, 0
	s_cmp_gt_u32 s49, 39
	s_cbranch_scc0 .LBB0_874
	s_lshl_b32 s82, s29, 19
	s_lshl_b32 s83, s10, 9
	s_add_u32 s80, s22, s82
	s_addc_u32 s81, s23, 0
	s_add_u32 s80, s80, s83
	s_addc_u32 s81, s81, 0
	v_and_b32_e32 v232, 15, v1
	s_lshr_b32 s82, s28, 2
	s_lshl_b32 s82, s82, 6
	v_lshrrev_b32_e32 v233, 4, v1
	v_add_u32_e32 v232, s82, v232
	s_and_b32 s83, s28, 3
	v_lshlrev_b32_e32 v233, 4, v233
	s_lshl_b32 s83, s83, 6
	v_lshlrev_b32_e32 v232, 11, v232
	v_add3_u32 v232, v232, v233, s83
	v_add_u32_e32 v164, s44, v150
	v_add_u32_e32 v180, s45, v150
	s_add_u32 s24, s12, s20
	ds_read_b128 v[152:155], v164
	ds_read_b128 v[156:159], v164 offset:1024
	ds_read_b128 v[160:163], v164 offset:2048
	ds_read_b128 v[164:167], v164 offset:3072
	ds_read_b128 v[168:171], v180
	ds_read_b128 v[172:175], v180 offset:1024
	ds_read_b128 v[176:179], v180 offset:2048
	ds_read_b128 v[180:183], v180 offset:3072
	s_addc_u32 s25, s13, s21
	s_add_u32 s24, s24, 0x100
	s_addc_u32 s25, s25, 0
	s_add_u32 s50, s17, s20
	s_addc_u32 s51, s48, s21
	s_cmpk_eq_i32 s20, 0x1500
	s_cselect_b32 s27, s19, s25
	s_cselect_b32 s26, s18, s24
	s_cselect_b32 s25, s7, s51
	s_cselect_b32 s24, s6, s50
	v_lshl_add_u64 v[208:209], v[146:147], 0, s[20:21]
	s_add_i32 m0, s37, 0xc000
	ds_read_b128 v[184:187], v151
	ds_read_b128 v[188:191], v151 offset:1024
	ds_read_b128 v[192:195], v151 offset:2048
	ds_read_b128 v[196:199], v151 offset:3072
	ds_read_b128 v[200:203], v151 offset:4096
	ds_read_b128 v[204:207], v151 offset:5120
	ds_read_b128 v[214:217], v151 offset:6144
	ds_read_b128 v[218:221], v151 offset:7168
	global_load_lds_dwordx4 v[208:209], off
	v_lshl_add_u64 v[208:209], v[148:149], 0, s[20:21]
	s_add_i32 m0, s37, 0xe000
	s_nop 0
	global_load_lds_dwordx4 v[208:209], off
	s_waitcnt vmcnt(8)
	s_waitcnt lgkmcnt(0)
	s_setprio 1
	s_waitcnt lgkmcnt(0)
	s_barrier
	v_mfma_f32_16x16x32_bf16 v[126:129], v[152:155], v[184:187], v[126:129]
	v_mfma_f32_16x16x32_bf16 v[122:125], v[160:163], v[184:187], v[122:125]
	v_mfma_f32_16x16x32_bf16 v[110:113], v[152:155], v[192:195], v[110:113]
	v_mfma_f32_16x16x32_bf16 v[106:109], v[160:163], v[192:195], v[106:109]
	v_mfma_f32_16x16x32_bf16 v[94:97], v[152:155], v[200:203], v[94:97]
	v_mfma_f32_16x16x32_bf16 v[90:93], v[160:163], v[200:203], v[90:93]
	v_mfma_f32_16x16x32_bf16 v[78:81], v[152:155], v[214:217], v[78:81]
	v_mfma_f32_16x16x32_bf16 v[74:77], v[160:163], v[214:217], v[74:77]
	v_mfma_f32_16x16x32_bf16 v[118:121], v[168:171], v[184:187], v[118:121]
	v_mfma_f32_16x16x32_bf16 v[114:117], v[176:179], v[184:187], v[114:117]
	v_mfma_f32_16x16x32_bf16 v[102:105], v[168:171], v[192:195], v[102:105]
	v_mfma_f32_16x16x32_bf16 v[98:101], v[176:179], v[192:195], v[98:101]
	v_mfma_f32_16x16x32_bf16 v[86:89], v[168:171], v[200:203], v[86:89]
	v_mfma_f32_16x16x32_bf16 v[82:85], v[176:179], v[200:203], v[82:85]
	v_mfma_f32_16x16x32_bf16 v[70:73], v[168:171], v[214:217], v[70:73]
	v_mfma_f32_16x16x32_bf16 v[66:69], v[176:179], v[214:217], v[66:69]
	v_mfma_f32_16x16x32_bf16 v[126:129], v[156:159], v[188:191], v[126:129]
	v_mfma_f32_16x16x32_bf16 v[122:125], v[164:167], v[188:191], v[122:125]
	v_mfma_f32_16x16x32_bf16 v[110:113], v[156:159], v[196:199], v[110:113]
	v_mfma_f32_16x16x32_bf16 v[106:109], v[164:167], v[196:199], v[106:109]
	v_mfma_f32_16x16x32_bf16 v[94:97], v[156:159], v[204:207], v[94:97]
	v_mfma_f32_16x16x32_bf16 v[90:93], v[164:167], v[204:207], v[90:93]
	v_mfma_f32_16x16x32_bf16 v[78:81], v[156:159], v[218:221], v[78:81]
	v_mfma_f32_16x16x32_bf16 v[74:77], v[164:167], v[218:221], v[74:77]
	v_mfma_f32_16x16x32_bf16 v[118:121], v[172:175], v[188:191], v[118:121]
	v_mfma_f32_16x16x32_bf16 v[114:117], v[180:183], v[188:191], v[114:117]
	v_mfma_f32_16x16x32_bf16 v[102:105], v[172:175], v[196:199], v[102:105]
	v_mfma_f32_16x16x32_bf16 v[98:101], v[180:183], v[196:199], v[98:101]
	v_mfma_f32_16x16x32_bf16 v[86:89], v[172:175], v[204:207], v[86:89]
	v_mfma_f32_16x16x32_bf16 v[82:85], v[180:183], v[204:207], v[82:85]
	v_mfma_f32_16x16x32_bf16 v[70:73], v[172:175], v[218:221], v[70:73]
	v_mfma_f32_16x16x32_bf16 v[66:69], v[180:183], v[218:221], v[66:69]
	s_setprio 0
	s_barrier
	s_add_i32 s50, s44, s36
	v_lshl_add_u64 v[208:209], s[24:25], 0, v[132:133]
	s_mov_b32 m0, s50
	ds_read_b128 v[184:187], v151 offset:16384
	ds_read_b128 v[188:191], v151 offset:17408
	ds_read_b128 v[192:195], v151 offset:18432
	ds_read_b128 v[196:199], v151 offset:19456
	ds_read_b128 v[200:203], v151 offset:20480
	ds_read_b128 v[204:207], v151 offset:21504
	ds_read_b128 v[214:217], v151 offset:22528
	ds_read_b128 v[218:221], v151 offset:23552
	s_add_u32 s84, s80, 0x0
	s_addc_u32 s85, s81, 0
	global_load_lds_dwordx4 v232, s[84:85]
	s_add_i32 m0, s50, 0x2000
	s_add_u32 s50, s24, 0xb0000
	v_lshl_add_u64 v[222:223], s[24:25], 0, v[136:137]
	s_addc_u32 s51, s25, 0
	s_add_i32 s56, s45, s36
	s_add_u32 s84, s80, 0x100
	s_addc_u32 s85, s81, 0
	global_load_lds_dwordx4 v232, s[84:85]
	v_lshl_add_u64 v[224:225], s[50:51], 0, v[132:133]
	s_mov_b32 m0, s56
	v_lshl_add_u64 v[226:227], s[26:27], 0, v[134:135]
	s_add_u32 s84, s80, 0x8000
	s_addc_u32 s85, s81, 0
	global_load_lds_dwordx4 v232, s[84:85]
	v_lshl_add_u64 v[224:225], s[50:51], 0, v[136:137]
	s_add_i32 m0, s56, 0x2000
	s_nop 0
	s_add_u32 s84, s80, 0x8100
	s_addc_u32 s85, s81, 0
	global_load_lds_dwordx4 v232, s[84:85]
	v_lshl_add_u64 v[224:225], s[26:27], 0, v[130:131]
	s_mov_b32 m0, s37
	s_nop 0
	s_add_u32 s84, s80, 0x10000
	s_addc_u32 s85, s81, 0
	global_load_lds_dwordx4 v232, s[84:85]
	s_mov_b32 m0, s38
	s_nop 0
	s_add_u32 s84, s80, 0x10100
	s_addc_u32 s85, s81, 0
	global_load_lds_dwordx4 v232, s[84:85]
	s_waitcnt vmcnt(8)
	s_waitcnt lgkmcnt(0)
	s_setprio 1
	s_waitcnt lgkmcnt(0)
	s_barrier
	v_mfma_f32_16x16x32_bf16 v[62:65], v[152:155], v[184:187], v[62:65]
	v_mfma_f32_16x16x32_bf16 v[58:61], v[160:163], v[184:187], v[58:61]
	v_mfma_f32_16x16x32_bf16 v[46:49], v[152:155], v[192:195], v[46:49]
	v_mfma_f32_16x16x32_bf16 v[42:45], v[160:163], v[192:195], v[42:45]
	v_mfma_f32_16x16x32_bf16 v[30:33], v[152:155], v[200:203], v[30:33]
	v_mfma_f32_16x16x32_bf16 v[26:29], v[160:163], v[200:203], v[26:29]
	v_mfma_f32_16x16x32_bf16 v[14:17], v[152:155], v[214:217], v[14:17]
	v_mfma_f32_16x16x32_bf16 v[10:13], v[160:163], v[214:217], v[10:13]
	v_mfma_f32_16x16x32_bf16 v[54:57], v[168:171], v[184:187], v[54:57]
	v_mfma_f32_16x16x32_bf16 v[50:53], v[176:179], v[184:187], v[50:53]
	v_mfma_f32_16x16x32_bf16 v[38:41], v[168:171], v[192:195], v[38:41]
	v_mfma_f32_16x16x32_bf16 v[34:37], v[176:179], v[192:195], v[34:37]
	v_mfma_f32_16x16x32_bf16 v[22:25], v[168:171], v[200:203], v[22:25]
	v_mfma_f32_16x16x32_bf16 v[18:21], v[176:179], v[200:203], v[18:21]
	v_mfma_f32_16x16x32_bf16 v[6:9], v[168:171], v[214:217], v[6:9]
	v_mfma_f32_16x16x32_bf16 v[2:5], v[176:179], v[214:217], v[2:5]
	v_mfma_f32_16x16x32_bf16 v[62:65], v[156:159], v[188:191], v[62:65]
	v_mfma_f32_16x16x32_bf16 v[58:61], v[164:167], v[188:191], v[58:61]
	v_mfma_f32_16x16x32_bf16 v[46:49], v[156:159], v[196:199], v[46:49]
	v_mfma_f32_16x16x32_bf16 v[42:45], v[164:167], v[196:199], v[42:45]
	v_mfma_f32_16x16x32_bf16 v[30:33], v[156:159], v[204:207], v[30:33]
	v_mfma_f32_16x16x32_bf16 v[26:29], v[164:167], v[204:207], v[26:29]
	v_mfma_f32_16x16x32_bf16 v[14:17], v[156:159], v[218:221], v[14:17]
	v_mfma_f32_16x16x32_bf16 v[10:13], v[164:167], v[218:221], v[10:13]
	v_mfma_f32_16x16x32_bf16 v[54:57], v[172:175], v[188:191], v[54:57]
	v_mfma_f32_16x16x32_bf16 v[50:53], v[180:183], v[188:191], v[50:53]
	v_mfma_f32_16x16x32_bf16 v[38:41], v[172:175], v[196:199], v[38:41]
	v_mfma_f32_16x16x32_bf16 v[34:37], v[180:183], v[196:199], v[34:37]
	v_mfma_f32_16x16x32_bf16 v[22:25], v[172:175], v[204:207], v[22:25]
	v_mfma_f32_16x16x32_bf16 v[18:21], v[180:183], v[204:207], v[18:21]
	v_mfma_f32_16x16x32_bf16 v[6:9], v[172:175], v[218:221], v[6:9]
	v_mfma_f32_16x16x32_bf16 v[2:5], v[180:183], v[218:221], v[2:5]
	s_setprio 0
	s_barrier
	s_add_i32 s50, 0, 0x18000
	s_add_i32 s51, 0, 0x1c000
	v_add_u32_e32 v164, s50, v150
	v_add_u32_e32 v180, s51, v150
	ds_read_b128 v[152:155], v164
	ds_read_b128 v[156:159], v164 offset:1024
	ds_read_b128 v[160:163], v164 offset:2048
	ds_read_b128 v[164:167], v164 offset:3072
	ds_read_b128 v[168:171], v180
	ds_read_b128 v[172:175], v180 offset:1024
	ds_read_b128 v[176:179], v180 offset:2048
	ds_read_b128 v[180:183], v180 offset:3072
	s_add_u32 s26, s26, 0xb0000
	s_addc_u32 s27, s27, 0
	s_mov_b32 m0, s39
	v_lshl_add_u64 v[228:229], s[26:27], 0, v[130:131]
	ds_read_b128 v[184:187], v151 offset:32768
	ds_read_b128 v[188:191], v151 offset:33792
	ds_read_b128 v[192:195], v151 offset:34816
	ds_read_b128 v[196:199], v151 offset:35840
	ds_read_b128 v[200:203], v151 offset:36864
	ds_read_b128 v[204:207], v151 offset:37888
	ds_read_b128 v[214:217], v151 offset:38912
	ds_read_b128 v[218:221], v151 offset:39936
	s_add_u32 s84, s80, 0x18000
	s_addc_u32 s85, s81, 0
	global_load_lds_dwordx4 v232, s[84:85]
	v_lshl_add_u64 v[228:229], s[26:27], 0, v[134:135]
	s_mov_b32 m0, s40
	s_nop 0
	s_add_u32 s84, s80, 0x18100
	s_addc_u32 s85, s81, 0
	global_load_lds_dwordx4 v232, s[84:85]
	s_waitcnt vmcnt(8)
	s_waitcnt lgkmcnt(0)
	s_setprio 1
	s_waitcnt lgkmcnt(0)
	s_barrier
	v_mfma_f32_16x16x32_bf16 v[126:129], v[152:155], v[184:187], v[126:129]
	v_mfma_f32_16x16x32_bf16 v[122:125], v[160:163], v[184:187], v[122:125]
	v_mfma_f32_16x16x32_bf16 v[110:113], v[152:155], v[192:195], v[110:113]
	v_mfma_f32_16x16x32_bf16 v[106:109], v[160:163], v[192:195], v[106:109]
	v_mfma_f32_16x16x32_bf16 v[94:97], v[152:155], v[200:203], v[94:97]
	v_mfma_f32_16x16x32_bf16 v[90:93], v[160:163], v[200:203], v[90:93]
	v_mfma_f32_16x16x32_bf16 v[78:81], v[152:155], v[214:217], v[78:81]
	v_mfma_f32_16x16x32_bf16 v[74:77], v[160:163], v[214:217], v[74:77]
	v_mfma_f32_16x16x32_bf16 v[118:121], v[168:171], v[184:187], v[118:121]
	v_mfma_f32_16x16x32_bf16 v[114:117], v[176:179], v[184:187], v[114:117]
	v_mfma_f32_16x16x32_bf16 v[102:105], v[168:171], v[192:195], v[102:105]
	v_mfma_f32_16x16x32_bf16 v[98:101], v[176:179], v[192:195], v[98:101]
	v_mfma_f32_16x16x32_bf16 v[86:89], v[168:171], v[200:203], v[86:89]
	v_mfma_f32_16x16x32_bf16 v[82:85], v[176:179], v[200:203], v[82:85]
	v_mfma_f32_16x16x32_bf16 v[70:73], v[168:171], v[214:217], v[70:73]
	v_mfma_f32_16x16x32_bf16 v[66:69], v[176:179], v[214:217], v[66:69]
	v_mfma_f32_16x16x32_bf16 v[126:129], v[156:159], v[188:191], v[126:129]
	v_mfma_f32_16x16x32_bf16 v[122:125], v[164:167], v[188:191], v[122:125]
	v_mfma_f32_16x16x32_bf16 v[110:113], v[156:159], v[196:199], v[110:113]
	v_mfma_f32_16x16x32_bf16 v[106:109], v[164:167], v[196:199], v[106:109]
	v_mfma_f32_16x16x32_bf16 v[94:97], v[156:159], v[204:207], v[94:97]
	v_mfma_f32_16x16x32_bf16 v[90:93], v[164:167], v[204:207], v[90:93]
	v_mfma_f32_16x16x32_bf16 v[78:81], v[156:159], v[218:221], v[78:81]
	v_mfma_f32_16x16x32_bf16 v[74:77], v[164:167], v[218:221], v[74:77]
	v_mfma_f32_16x16x32_bf16 v[118:121], v[172:175], v[188:191], v[118:121]
	v_mfma_f32_16x16x32_bf16 v[114:117], v[180:183], v[188:191], v[114:117]
	v_mfma_f32_16x16x32_bf16 v[102:105], v[172:175], v[196:199], v[102:105]
	v_mfma_f32_16x16x32_bf16 v[98:101], v[180:183], v[196:199], v[98:101]
	v_mfma_f32_16x16x32_bf16 v[86:89], v[172:175], v[204:207], v[86:89]
	v_mfma_f32_16x16x32_bf16 v[82:85], v[180:183], v[204:207], v[82:85]
	v_mfma_f32_16x16x32_bf16 v[70:73], v[172:175], v[218:221], v[70:73]
	v_mfma_f32_16x16x32_bf16 v[66:69], v[180:183], v[218:221], v[66:69]
	s_setprio 0
	s_barrier
	s_add_i32 s26, s50, s36
	v_lshl_add_u64 v[208:209], v[208:209], 0, s[14:15]
	s_mov_b32 m0, s26
	ds_read_b128 v[184:187], v151 offset:49152
	ds_read_b128 v[188:191], v151 offset:50176
	ds_read_b128 v[192:195], v151 offset:51200
	ds_read_b128 v[196:199], v151 offset:52224
	ds_read_b128 v[200:203], v151 offset:53248
	ds_read_b128 v[204:207], v151 offset:54272
	ds_read_b128 v[214:217], v151 offset:55296
	ds_read_b128 v[218:221], v151 offset:56320
	s_add_u32 s84, s80, 0x40000
	s_addc_u32 s85, s81, 0
	global_load_lds_dwordx4 v232, s[84:85]
	s_add_i32 m0, s26, 0x2000
	s_add_u32 s24, s24, 0xb0080
	v_lshl_add_u64 v[208:209], v[222:223], 0, s[14:15]
	s_addc_u32 s25, s25, 0
	s_add_i32 s26, s51, s36
	s_add_u32 s84, s80, 0x40100
	s_addc_u32 s85, s81, 0
	global_load_lds_dwordx4 v232, s[84:85]
	v_lshl_add_u64 v[208:209], s[24:25], 0, v[132:133]
	s_mov_b32 m0, s26
	s_nop 0
	s_add_u32 s84, s80, 0x48000
	s_addc_u32 s85, s81, 0
	global_load_lds_dwordx4 v232, s[84:85]
	v_lshl_add_u64 v[208:209], s[24:25], 0, v[136:137]
	s_add_i32 m0, s26, 0x2000
	s_nop 0
	s_add_u32 s84, s80, 0x48100
	s_addc_u32 s85, s81, 0
	global_load_lds_dwordx4 v232, s[84:85]
	v_lshl_add_u64 v[208:209], v[224:225], 0, s[14:15]
	s_mov_b32 m0, s41
	s_nop 0
	s_add_u32 s84, s80, 0x50000
	s_addc_u32 s85, s81, 0
	global_load_lds_dwordx4 v232, s[84:85]
	v_lshl_add_u64 v[208:209], v[226:227], 0, s[14:15]
	s_mov_b32 m0, s42
	s_nop 0
	s_add_u32 s84, s80, 0x50100
	s_addc_u32 s85, s81, 0
	global_load_lds_dwordx4 v232, s[84:85]
	s_waitcnt vmcnt(8)
	s_waitcnt lgkmcnt(0)
	s_setprio 1
	s_waitcnt lgkmcnt(0)
	s_barrier
	v_mfma_f32_16x16x32_bf16 v[62:65], v[152:155], v[184:187], v[62:65]
	v_mfma_f32_16x16x32_bf16 v[58:61], v[160:163], v[184:187], v[58:61]
	v_mfma_f32_16x16x32_bf16 v[46:49], v[152:155], v[192:195], v[46:49]
	v_mfma_f32_16x16x32_bf16 v[42:45], v[160:163], v[192:195], v[42:45]
	v_mfma_f32_16x16x32_bf16 v[30:33], v[152:155], v[200:203], v[30:33]
	v_mfma_f32_16x16x32_bf16 v[26:29], v[160:163], v[200:203], v[26:29]
	v_mfma_f32_16x16x32_bf16 v[14:17], v[152:155], v[214:217], v[14:17]
	v_mfma_f32_16x16x32_bf16 v[10:13], v[160:163], v[214:217], v[10:13]
	v_mfma_f32_16x16x32_bf16 v[54:57], v[168:171], v[184:187], v[54:57]
	v_mfma_f32_16x16x32_bf16 v[50:53], v[176:179], v[184:187], v[50:53]
	v_mfma_f32_16x16x32_bf16 v[38:41], v[168:171], v[192:195], v[38:41]
	v_mfma_f32_16x16x32_bf16 v[34:37], v[176:179], v[192:195], v[34:37]
	v_mfma_f32_16x16x32_bf16 v[22:25], v[168:171], v[200:203], v[22:25]
	v_mfma_f32_16x16x32_bf16 v[18:21], v[176:179], v[200:203], v[18:21]
	v_mfma_f32_16x16x32_bf16 v[6:9], v[168:171], v[214:217], v[6:9]
	v_mfma_f32_16x16x32_bf16 v[2:5], v[176:179], v[214:217], v[2:5]
	v_mfma_f32_16x16x32_bf16 v[62:65], v[156:159], v[188:191], v[62:65]
	v_mfma_f32_16x16x32_bf16 v[58:61], v[164:167], v[188:191], v[58:61]
	v_mfma_f32_16x16x32_bf16 v[46:49], v[156:159], v[196:199], v[46:49]
	v_mfma_f32_16x16x32_bf16 v[42:45], v[164:167], v[196:199], v[42:45]
	v_mfma_f32_16x16x32_bf16 v[30:33], v[156:159], v[204:207], v[30:33]
	v_mfma_f32_16x16x32_bf16 v[26:29], v[164:167], v[204:207], v[26:29]
	v_mfma_f32_16x16x32_bf16 v[14:17], v[156:159], v[218:221], v[14:17]
	v_mfma_f32_16x16x32_bf16 v[10:13], v[164:167], v[218:221], v[10:13]
	v_mfma_f32_16x16x32_bf16 v[54:57], v[172:175], v[188:191], v[54:57]
	v_mfma_f32_16x16x32_bf16 v[50:53], v[180:183], v[188:191], v[50:53]
	v_mfma_f32_16x16x32_bf16 v[38:41], v[172:175], v[196:199], v[38:41]
	v_mfma_f32_16x16x32_bf16 v[34:37], v[180:183], v[196:199], v[34:37]
	v_mfma_f32_16x16x32_bf16 v[22:25], v[172:175], v[204:207], v[22:25]
	v_mfma_f32_16x16x32_bf16 v[18:21], v[180:183], v[204:207], v[18:21]
	v_mfma_f32_16x16x32_bf16 v[6:9], v[172:175], v[218:221], v[6:9]
	v_mfma_f32_16x16x32_bf16 v[2:5], v[180:183], v[218:221], v[2:5]
	s_setprio 0
	s_barrier
	s_add_i32 s49, s49, 2
	s_add_u32 s20, s20, 0x100
	s_addc_u32 s21, s21, 0
	s_add_u32 s20, s17, 0xffffff00
	s_addc_u32 s21, s48, -1
	s_and_b64 vcc, exec, s[4:5]
	s_cbranch_vccnz .LBB0_877
	v_mov_b32_e32 v2, 0
	s_mov_b32 s10, s46
	s_mov_b32 s29, s47
	s_mov_b64 s[12:13], s[18:19]
	s_mov_b32 s43, s16
	v_mov_b32_e32 v3, v2
	v_mov_b32_e32 v4, v2
	v_mov_b32_e32 v5, v2
	v_mov_b32_e32 v6, v2
	v_mov_b32_e32 v7, v2
	v_mov_b32_e32 v8, v2
	v_mov_b32_e32 v9, v2
	v_mov_b32_e32 v18, v2
	v_mov_b32_e32 v19, v2
	v_mov_b32_e32 v20, v2
	v_mov_b32_e32 v21, v2
	v_mov_b32_e32 v22, v2
	v_mov_b32_e32 v23, v2
	v_mov_b32_e32 v24, v2
	v_mov_b32_e32 v25, v2
	v_mov_b32_e32 v34, v2
	v_mov_b32_e32 v35, v2
	v_mov_b32_e32 v36, v2
	v_mov_b32_e32 v37, v2
	v_mov_b32_e32 v38, v2
	v_mov_b32_e32 v39, v2
	v_mov_b32_e32 v40, v2
	v_mov_b32_e32 v41, v2
	v_mov_b32_e32 v50, v2
	v_mov_b32_e32 v51, v2
	v_mov_b32_e32 v52, v2
	v_mov_b32_e32 v53, v2
	v_mov_b32_e32 v54, v2
	v_mov_b32_e32 v55, v2
	v_mov_b32_e32 v56, v2
	v_mov_b32_e32 v57, v2
	v_mov_b32_e32 v10, v2
	v_mov_b32_e32 v11, v2
	v_mov_b32_e32 v12, v2
	v_mov_b32_e32 v13, v2
	v_mov_b32_e32 v14, v2
	v_mov_b32_e32 v15, v2
	v_mov_b32_e32 v16, v2
	v_mov_b32_e32 v17, v2
	v_mov_b32_e32 v26, v2
	v_mov_b32_e32 v27, v2
	v_mov_b32_e32 v28, v2
	v_mov_b32_e32 v29, v2
	v_mov_b32_e32 v30, v2
	v_mov_b32_e32 v31, v2
	v_mov_b32_e32 v32, v2
	v_mov_b32_e32 v33, v2
	v_mov_b32_e32 v42, v2
	v_mov_b32_e32 v43, v2
	v_mov_b32_e32 v44, v2
	v_mov_b32_e32 v45, v2
	v_mov_b32_e32 v46, v2
	v_mov_b32_e32 v47, v2
	v_mov_b32_e32 v48, v2
	v_mov_b32_e32 v49, v2
	v_mov_b32_e32 v58, v2
	v_mov_b32_e32 v59, v2
	v_mov_b32_e32 v60, v2
	v_mov_b32_e32 v61, v2
	v_mov_b32_e32 v62, v2
	v_mov_b32_e32 v63, v2
	v_mov_b32_e32 v64, v2
	v_mov_b32_e32 v65, v2
	v_mov_b32_e32 v66, v2
	v_mov_b32_e32 v67, v2
	v_mov_b32_e32 v68, v2
	v_mov_b32_e32 v69, v2
	v_mov_b32_e32 v70, v2
	v_mov_b32_e32 v71, v2
	v_mov_b32_e32 v72, v2
	v_mov_b32_e32 v73, v2
	v_mov_b32_e32 v82, v2
	v_mov_b32_e32 v83, v2
	v_mov_b32_e32 v84, v2
	v_mov_b32_e32 v85, v2
	v_mov_b32_e32 v86, v2
	v_mov_b32_e32 v87, v2
	v_mov_b32_e32 v88, v2
	v_mov_b32_e32 v89, v2
	v_mov_b32_e32 v98, v2
	v_mov_b32_e32 v99, v2
	v_mov_b32_e32 v100, v2
	v_mov_b32_e32 v101, v2
	v_mov_b32_e32 v102, v2
	v_mov_b32_e32 v103, v2
	v_mov_b32_e32 v104, v2
	v_mov_b32_e32 v105, v2
	v_mov_b32_e32 v114, v2
	v_mov_b32_e32 v115, v2
	v_mov_b32_e32 v116, v2
	v_mov_b32_e32 v117, v2
	v_mov_b32_e32 v118, v2
	v_mov_b32_e32 v119, v2
	v_mov_b32_e32 v120, v2
	v_mov_b32_e32 v121, v2
	v_mov_b32_e32 v74, v2
	v_mov_b32_e32 v75, v2
	v_mov_b32_e32 v76, v2
	v_mov_b32_e32 v77, v2
	v_mov_b32_e32 v78, v2
	v_mov_b32_e32 v79, v2
	v_mov_b32_e32 v80, v2
	v_mov_b32_e32 v81, v2
	v_mov_b32_e32 v90, v2
	v_mov_b32_e32 v91, v2
	v_mov_b32_e32 v92, v2
	v_mov_b32_e32 v93, v2
	v_mov_b32_e32 v94, v2
	v_mov_b32_e32 v95, v2
	v_mov_b32_e32 v96, v2
	v_mov_b32_e32 v97, v2
	v_mov_b32_e32 v106, v2
	v_mov_b32_e32 v107, v2
	v_mov_b32_e32 v108, v2
	v_mov_b32_e32 v109, v2
	v_mov_b32_e32 v110, v2
	v_mov_b32_e32 v111, v2
	v_mov_b32_e32 v112, v2
	v_mov_b32_e32 v113, v2
	v_mov_b32_e32 v122, v2
	v_mov_b32_e32 v123, v2
	v_mov_b32_e32 v124, v2
	v_mov_b32_e32 v125, v2
	v_mov_b32_e32 v126, v2
	v_mov_b32_e32 v127, v2
	v_mov_b32_e32 v128, v2
	v_mov_b32_e32 v129, v2
	s_andn2_b64 vcc, exec, s[0:1]
	s_cbranch_vccnz .LBB0_878
	s_branch .LBB0_879
